# pool-mix group map: weights loaded once per phase per wave, p rows streamed from LDS three reads deep; pooling tasks spread so the third round lands on 144 different CUs
# speedup vs baseline: 1.0548x; 1.0076x over previous
; __device__ __forceinline__ int opaque_tid() { int t = threadIdx.x; asm volatile("" : "+v"(t)); return t; }
; template <int MODE>
; __device__ __forceinline__ void poolconv_wave(const Ctx& C, int l, int ch, int g, int lane, float* PL) {
;     constexpr bool samp = (MODE == 2);
;     const int b = samp ? ch - 1028 : ch / 257, t0 = samp ? 0 : 16 * (ch % 257);
;     const size_t rowbase = samp ? (size_t)NPR + 16 * b : (size_t)b * TP + t0;
;     const int pos0 = samp ? 1024 : 0, c = 64 * g + lane, wnd = 2 << g;
;     const float* spool = C.in[4] + ((size_t)l * 32 + b) * 15 * 256;
;     const float* sconv = C.in[5] + ((size_t)l * 32 + b) * 2 * 256;
; __device__ __forceinline__ void mixers_phase(const Ctx& C, int l, unsigned char* shm, int sub) {
;     ...
;     if (sub & 4) {
;         const int tid = opaque_tid(), lane = tid & 63, gw = blockIdx.x * 8 + __builtin_amdgcn_readfirstlane(tid >> 6), NGW = G * 8;
;     ...
;         for (int u = gw; u < 4240; u += NGW) {
;             const int ch = u >> 2, g = u & 3; float* PL = (float*)shm + (tid >> 6) * 1024;
;             if (ch >= 1028) poolconv_wave<2>(C, l, ch, g, lane, PL);
;             else if (ch % 257 == 0) poolconv_wave<1>(C, l, ch, g, lane, PL);
;             else poolconv_wave<0>(C, l, ch, g, lane, PL);
;         }
.LBB0_619:
	v_mov_b32_e32 v0, v195
	v_readlane_b32 s1, v252, 0
	v_ashrrev_i32_e32 v2, 6, v0
	s_nop 0
	v_readfirstlane_b32 s0, v2
	s_waitcnt lgkmcnt(0)
	s_mul_i32 s58, s0, s47
	s_add_i32 s58, s58, s1
	s_cmpk_gt_i32 s58, 0x108f
	s_cbranch_scc1 .LBB0_826
	v_readlane_b32 s2, v254, 51
	v_readlane_b32 s3, v254, 52
	s_mov_b32 s16, s2
	s_ashr_i32 s17, s2, 31
	s_mul_i32 s1, s2, 0x300
	s_and_b32 s14, s58, 3
	s_waitcnt lgkmcnt(0)
	s_lshl_b32 s59, s47, 3
	s_lshl_b64 s[4:5], s[16:17], 2
	s_add_i32 s2, s1, 0x100
	s_add_i32 s3, s1, 0x200
	s_lshl_b64 s[6:7], s[16:17], 5
	s_lshl_b32 s60, 2, s14
	s_cmp_lg_u32 s14, 0
	s_cselect_b64 s[8:9], -1, 0
	s_cmp_gt_u32 s14, 1
	s_cselect_b64 s[10:11], -1, 0
	s_cmp_eq_u32 s14, 3
	s_cselect_b64 s[12:13], -1, 0
	s_min_u32 s0, s60, 3
	v_cvt_f32_ubyte0_e32 v118, s0
	s_min_u32 s0, s60, 4
	v_cvt_f32_ubyte0_e32 v119, s0
	s_min_u32 s0, s60, 5
	v_cvt_f32_ubyte0_e32 v120, s0
	s_min_u32 s0, s60, 6
	v_cvt_f32_ubyte0_e32 v121, s0
	s_min_u32 s0, s60, 7
	v_cvt_f32_ubyte0_e32 v122, s0
	s_min_u32 s0, s60, 8
	v_cvt_f32_ubyte0_e32 v123, s0
	s_min_u32 s0, s60, 9
	v_cvt_f32_ubyte0_e32 v124, s0
	s_min_u32 s0, s60, 10
	v_cvt_f32_ubyte0_e32 v125, s0
	s_min_u32 s0, s60, 11
	v_cvt_f32_ubyte0_e32 v126, s0
	s_min_u32 s0, s60, 12
	v_cvt_f32_ubyte0_e32 v127, s0
	s_min_u32 s0, s60, 13
	v_and_b32_e32 v0, 63, v0
	v_cvt_f32_ubyte0_e32 v128, s0
	s_min_u32 s0, s60, 14
	v_lshl_add_u32 v116, v2, 12, 0
	v_lshlrev_b32_e32 v2, 2, v0
	v_lshl_or_b32 v0, s14, 6, v0
	v_cvt_f32_ubyte0_e32 v129, s0
	s_min_u32 s0, s60, 15
	v_or_b32_e32 v6, s1, v0
	v_or_b32_e32 v8, s2, v0
	v_cvt_f32_ubyte0_e32 v130, s0
	v_lshlrev_b32_e32 v12, 2, v0
	v_mov_b32_e32 v13, v1
	v_readlane_b32 s36, v252, 21
	s_lshl_b64 s[0:1], s[16:17], 16
	s_lshl_b32 s2, s14, 14
	v_or_b32_e32 v10, s3, v0
	v_lshl_add_u64 v[36:37], s[80:81], 0, v[12:13]
	v_lshl_add_u64 v[38:39], s[82:83], 0, v[12:13]
	v_readlane_b32 s46, v252, 31
	v_readlane_b32 s72, v252, 39
	s_or_b32 s0, s0, s2
	v_lshl_or_b32 v4, s16, 8, v0
	v_ashrrev_i32_e32 v7, 31, v6
	v_ashrrev_i32_e32 v9, 31, v8
	v_ashrrev_i32_e32 v11, 31, v10
	v_readlane_b32 s20, v254, 21
	v_readlane_b32 s47, v252, 32
	v_readlane_b32 s73, v252, 40
	v_readlane_b32 s74, v252, 41
	v_readlane_b32 s75, v252, 42
	v_readlane_b32 s76, v252, 43
	v_readlane_b32 s77, v252, 44
	v_readlane_b32 s78, v252, 45
	v_readlane_b32 s79, v252, 46
	v_readlane_b32 s80, v252, 47
	v_readlane_b32 s81, v252, 48
	v_readlane_b32 s82, v252, 49
	v_readlane_b32 s83, v252, 50
	v_readlane_b32 s84, v252, 51
	v_readlane_b32 s85, v252, 52
	v_readlane_b32 s86, v252, 53
	v_readlane_b32 s87, v252, 54
	s_add_u32 s0, s46, s0
	v_ashrrev_i32_e32 v5, 31, v4
	v_readlane_b32 s24, v254, 25
	v_readlane_b32 s25, v254, 26
	v_lshlrev_b32_e32 v14, 1, v0
	v_mov_b32_e32 v15, v1
	v_readlane_b32 s48, v252, 33
	v_readlane_b32 s49, v252, 34
	v_lshl_add_u64 v[44:45], v[6:7], 2, s[72:73]
	v_lshl_add_u64 v[46:47], v[8:9], 2, s[72:73]
	v_lshl_add_u64 v[48:49], v[10:11], 2, s[72:73]
	v_readlane_b32 s72, v254, 53
	v_mov_b32_e32 v3, v1
	s_addc_u32 s1, s47, s1
	v_add_u32_e32 v117, v116, v2
	v_cvt_f32_ubyte0_e32 v131, s60
	v_lshl_add_u64 v[32:33], s[24:25], 0, v[12:13]
	v_lshl_add_u64 v[34:35], s[70:71], 0, v[14:15]
	v_lshl_add_u64 v[40:41], s[94:95], 0, v[14:15]
	v_lshl_add_u64 v[42:43], v[4:5], 2, s[48:49]
	v_readlane_b32 s73, v254, 54
	v_readlane_b32 s74, v254, 55
	v_readlane_b32 s75, v254, 56
	v_readlane_b32 s76, v254, 57
	v_readlane_b32 s77, v254, 58
	v_readlane_b32 s78, v254, 59
	v_readlane_b32 s79, v254, 60
	v_readlane_b32 s80, v254, 61
	v_readlane_b32 s81, v254, 62
	v_readlane_b32 s82, v254, 63
	v_readlane_b32 s83, v251, 0
	v_readlane_b32 s84, v251, 1
	v_readlane_b32 s85, v251, 2
	v_readlane_b32 s86, v251, 3
	v_readlane_b32 s87, v251, 4
	v_lshl_add_u64 v[50:51], s[0:1], 0, v[2:3]
	s_mov_b64 s[20:21], s[0:1]
; template <int MODE>
; __device__ __forceinline__ void poolconv_wave(const Ctx& C, int l, int ch, int g, int lane, float* PL) {
;     ...
;     const float* wp = C.in[13] + ((size_t)l * 4 + g) * 4096 + lane;
; #pragma unroll
;     for (int i = 0; i < 16; ++i) PL[i * 64 + lane] = p[i];
;     asm volatile("s_waitcnt lgkmcnt(0)" ::: "memory");
; #pragma unroll 2
;     for (int k4 = 0; k4 < 16; ++k4) {
;         const float w0 = wp[(4 * k4 + 0) * 64], w1 = wp[(4 * k4 + 1) * 64], w2 = wp[(4 * k4 + 2) * 64], w3 = wp[(4 * k4 + 3) * 64];
; #pragma unroll
;         for (int i = 0; i < 16; ++i) { const f32x4 pv = *(const f32x4*)(PL + i * 64 + 4 * k4); acc[i] += pv[0] * w0 + pv[1] * w1 + pv[2] * w2 + pv[3] * w3; }
	global_load_dword v146, v2, s[20:21]
	global_load_dword v147, v2, s[20:21] offset:256
	global_load_dword v148, v2, s[20:21] offset:512
	global_load_dword v149, v2, s[20:21] offset:768
	global_load_dword v150, v2, s[20:21] offset:1024
	global_load_dword v151, v2, s[20:21] offset:1280
	global_load_dword v152, v2, s[20:21] offset:1536
	global_load_dword v153, v2, s[20:21] offset:1792
	global_load_dword v154, v2, s[20:21] offset:2048
	global_load_dword v155, v2, s[20:21] offset:2304
	global_load_dword v156, v2, s[20:21] offset:2560
	global_load_dword v157, v2, s[20:21] offset:2816
	global_load_dword v158, v2, s[20:21] offset:3072
	global_load_dword v159, v2, s[20:21] offset:3328
	global_load_dword v160, v2, s[20:21] offset:3584
	global_load_dword v161, v2, s[20:21] offset:3840
	s_add_u32 s20, s20, 0x1000
	s_addc_u32 s21, s21, 0
	global_load_dword v162, v2, s[20:21]
	global_load_dword v163, v2, s[20:21] offset:256
	global_load_dword v164, v2, s[20:21] offset:512
	global_load_dword v165, v2, s[20:21] offset:768
	global_load_dword v184, v2, s[20:21] offset:1024
	global_load_dword v185, v2, s[20:21] offset:1280
	global_load_dword v186, v2, s[20:21] offset:1536
	global_load_dword v187, v2, s[20:21] offset:1792
	global_load_dword v188, v2, s[20:21] offset:2048
	global_load_dword v189, v2, s[20:21] offset:2304
	global_load_dword v190, v2, s[20:21] offset:2560
	global_load_dword v191, v2, s[20:21] offset:2816
	global_load_dword v192, v2, s[20:21] offset:3072
	global_load_dword v193, v2, s[20:21] offset:3328
	global_load_dword v196, v2, s[20:21] offset:3584
	global_load_dword v197, v2, s[20:21] offset:3840
	s_add_u32 s20, s20, 0x1000
	s_addc_u32 s21, s21, 0
	global_load_dword v198, v2, s[20:21]
	global_load_dword v199, v2, s[20:21] offset:256
	global_load_dword v200, v2, s[20:21] offset:512
	global_load_dword v201, v2, s[20:21] offset:768
	global_load_dword v202, v2, s[20:21] offset:1024
	global_load_dword v203, v2, s[20:21] offset:1280
	global_load_dword v204, v2, s[20:21] offset:1536
	global_load_dword v205, v2, s[20:21] offset:1792
	global_load_dword v206, v2, s[20:21] offset:2048
	global_load_dword v207, v2, s[20:21] offset:2304
	global_load_dword v208, v2, s[20:21] offset:2560
	global_load_dword v209, v2, s[20:21] offset:2816
	global_load_dword v210, v2, s[20:21] offset:3072
	global_load_dword v211, v2, s[20:21] offset:3328
	global_load_dword v212, v2, s[20:21] offset:3584
	global_load_dword v213, v2, s[20:21] offset:3840
	s_add_u32 s20, s20, 0x1000
	s_addc_u32 s21, s21, 0
	global_load_dword v214, v2, s[20:21]
	global_load_dword v215, v2, s[20:21] offset:256
	global_load_dword v216, v2, s[20:21] offset:512
	global_load_dword v217, v2, s[20:21] offset:768
	global_load_dword v218, v2, s[20:21] offset:1024
	global_load_dword v219, v2, s[20:21] offset:1280
	global_load_dword v220, v2, s[20:21] offset:1536
	global_load_dword v221, v2, s[20:21] offset:1792
	global_load_dword v222, v2, s[20:21] offset:2048
	global_load_dword v223, v2, s[20:21] offset:2304
	global_load_dword v224, v2, s[20:21] offset:2560
	global_load_dword v225, v2, s[20:21] offset:2816
	global_load_dword v226, v2, s[20:21] offset:3072
	global_load_dword v227, v2, s[20:21] offset:3328
	global_load_dword v228, v2, s[20:21] offset:3584
	global_load_dword v229, v2, s[20:21] offset:3840
	v_readlane_b32 s21, v254, 22
	v_readlane_b32 s22, v254, 23
	v_readlane_b32 s23, v254, 24
	v_readlane_b32 s26, v254, 27
	v_readlane_b32 s27, v254, 28
	v_readlane_b32 s37, v252, 22
	v_readlane_b32 s38, v252, 23
	v_readlane_b32 s39, v252, 24
	v_readlane_b32 s40, v252, 25
	v_readlane_b32 s41, v252, 26
	v_readlane_b32 s42, v252, 27
	v_readlane_b32 s43, v252, 28
	v_readlane_b32 s44, v252, 29
	v_readlane_b32 s45, v252, 30
	v_readlane_b32 s50, v252, 35
	v_readlane_b32 s51, v252, 36
	s_branch .LBB0_622

; template <int MODE>
; __device__ __forceinline__ void poolconv_wave(const Ctx& C, int l, int ch, int g, int lane, float* PL) {
;     ...
;     float p[16], acc[16];
; #pragma unroll
;     for (int i = 0; i < 16; ++i) { const int pos = pos0 + t0 + i; p[i] = s[15 + i] / (float)min(pos + 1, wnd) - a[i]; acc[i] = 0.f; }
.LBB0_632:
	s_or_b32 s21, s20, 1
	s_min_i32 s21, s21, s60
	v_cvt_f32_i32_e32 v5, s21
	s_or_b32 s21, s20, 2
	s_min_i32 s21, s21, s60
	v_cvt_f32_i32_e32 v9, s21
	v_div_scale_f32 v7, s[26:27], v5, v5, v110
	v_rcp_f32_e32 v8, v7
	v_div_scale_f32 v10, vcc, v110, v5, v110
	s_or_b32 s21, s20, 3
	v_fma_f32 v11, -v7, v8, 1.0
	v_fmac_f32_e32 v8, v11, v8
	v_mul_f32_e32 v11, v10, v8
	v_fma_f32 v12, -v7, v11, v10
	v_fmac_f32_e32 v11, v12, v8
	v_fma_f32 v7, -v7, v11, v10
	v_div_scale_f32 v10, s[26:27], v9, v9, v111
	v_rcp_f32_e32 v12, v10
	v_div_fmas_f32 v7, v7, v8, v11
	v_div_fixup_f32 v5, v7, v5, v110
	s_min_i32 s21, s21, s60
	v_sub_f32_e32 v4, v5, v4
	v_fma_f32 v5, -v10, v12, 1.0
	v_cvt_f32_i32_e32 v11, s21
	v_fmac_f32_e32 v12, v5, v12
	v_div_scale_f32 v5, vcc, v111, v9, v111
	v_mul_f32_e32 v7, v5, v12
	v_fma_f32 v8, -v10, v7, v5
	v_fmac_f32_e32 v7, v8, v12
	v_div_scale_f32 v8, s[26:27], v11, v11, v108
	v_fma_f32 v5, -v10, v7, v5
	v_rcp_f32_e32 v10, v8
	s_or_b32 s21, s20, 4
	v_div_fmas_f32 v5, v5, v12, v7
	s_min_i32 s21, s21, s60
	v_fma_f32 v7, -v8, v10, 1.0
	v_fmac_f32_e32 v10, v7, v10
	v_div_scale_f32 v7, vcc, v108, v11, v108
	v_cvt_f32_i32_e32 v13, s21
	v_div_fixup_f32 v5, v5, v9, v111
	v_mul_f32_e32 v9, v7, v10
	v_fma_f32 v12, -v8, v9, v7
	v_fmac_f32_e32 v9, v12, v10
	v_fma_f32 v7, -v8, v9, v7
	v_div_scale_f32 v8, s[26:27], v13, v13, v109
	v_rcp_f32_e32 v12, v8
	s_or_b32 s21, s20, 5
	v_div_fmas_f32 v7, v7, v10, v9
	s_min_i32 s21, s21, s60
	v_fma_f32 v9, -v8, v12, 1.0
	v_fmac_f32_e32 v12, v9, v12
	v_div_scale_f32 v9, vcc, v109, v13, v109
	v_cvt_f32_i32_e32 v14, s21
	v_mul_f32_e32 v10, v9, v12
	v_div_fixup_f32 v7, v7, v11, v108
	v_fma_f32 v11, -v8, v10, v9
	v_fmac_f32_e32 v10, v11, v12
	v_fma_f32 v8, -v8, v10, v9
	v_div_scale_f32 v9, s[26:27], v14, v14, v106
	v_rcp_f32_e32 v11, v9
	s_or_b32 s21, s20, 6
	v_div_fmas_f32 v8, v8, v12, v10
	s_min_i32 s21, s21, s60
	v_fma_f32 v10, -v9, v11, 1.0
	v_fmac_f32_e32 v11, v10, v11
	v_div_scale_f32 v10, vcc, v106, v14, v106
	v_cvt_f32_i32_e32 v15, s21
	v_mul_f32_e32 v12, v10, v11
	v_div_fixup_f32 v8, v8, v13, v109
	v_fma_f32 v13, -v9, v12, v10
	v_fmac_f32_e32 v12, v13, v11
	v_fma_f32 v9, -v9, v12, v10
	v_div_scale_f32 v10, s[26:27], v15, v15, v107
	v_rcp_f32_e32 v13, v10
	s_or_b32 s21, s20, 7
	v_div_fmas_f32 v9, v9, v11, v12
	s_min_i32 s21, s21, s60
	v_fma_f32 v11, -v10, v13, 1.0
	v_fmac_f32_e32 v13, v11, v13
	v_div_scale_f32 v11, vcc, v107, v15, v107
	v_cvt_f32_i32_e32 v16, s21
	v_mul_f32_e32 v12, v11, v13
	v_div_fixup_f32 v9, v9, v14, v106
	v_fma_f32 v14, -v10, v12, v11
	v_fmac_f32_e32 v12, v14, v13
	v_fma_f32 v10, -v10, v12, v11
	v_div_scale_f32 v11, s[26:27], v16, v16, v104
	v_rcp_f32_e32 v14, v11
	s_or_b32 s21, s20, 8
	v_div_fmas_f32 v10, v10, v13, v12
	s_min_i32 s21, s21, s60
	v_fma_f32 v12, -v11, v14, 1.0
	v_fmac_f32_e32 v14, v12, v14
	v_div_scale_f32 v12, vcc, v104, v16, v104
	v_cvt_f32_i32_e32 v17, s21
	v_mul_f32_e32 v13, v12, v14
	v_div_fixup_f32 v10, v10, v15, v107
	v_fma_f32 v15, -v11, v13, v12
	v_fmac_f32_e32 v13, v15, v14
	v_fma_f32 v11, -v11, v13, v12
	v_div_scale_f32 v12, s[26:27], v17, v17, v105
	v_rcp_f32_e32 v15, v12
	s_or_b32 s21, s20, 9
	v_div_fmas_f32 v11, v11, v14, v13
	s_min_i32 s21, s21, s60
	v_fma_f32 v13, -v12, v15, 1.0
	v_fmac_f32_e32 v15, v13, v15
	v_div_scale_f32 v13, vcc, v105, v17, v105
	v_cvt_f32_i32_e32 v18, s21
	v_mul_f32_e32 v14, v13, v15
	v_div_fixup_f32 v11, v11, v16, v104
	v_fma_f32 v16, -v12, v14, v13
	v_fmac_f32_e32 v14, v16, v15
	v_fma_f32 v12, -v12, v14, v13
	v_div_scale_f32 v13, s[26:27], v18, v18, v102
	v_rcp_f32_e32 v16, v13
	s_or_b32 s21, s20, 10
	v_div_fmas_f32 v12, v12, v15, v14
	s_min_i32 s21, s21, s60
	v_fma_f32 v14, -v13, v16, 1.0
	v_fmac_f32_e32 v16, v14, v16
	v_div_scale_f32 v14, vcc, v102, v18, v102
	v_cvt_f32_i32_e32 v19, s21
	v_mul_f32_e32 v15, v14, v16
	v_div_fixup_f32 v12, v12, v17, v105
	v_fma_f32 v17, -v13, v15, v14
	v_fmac_f32_e32 v15, v17, v16
	v_fma_f32 v13, -v13, v15, v14
	v_div_scale_f32 v14, s[26:27], v19, v19, v103
	v_rcp_f32_e32 v17, v14
	s_or_b32 s21, s20, 11
	v_div_fmas_f32 v13, v13, v16, v15
	s_min_i32 s21, s21, s60
	v_fma_f32 v15, -v14, v17, 1.0
	v_fmac_f32_e32 v17, v15, v17
	v_div_scale_f32 v15, vcc, v103, v19, v103
	v_cvt_f32_i32_e32 v20, s21
	v_mul_f32_e32 v16, v15, v17
	v_div_fixup_f32 v13, v13, v18, v102
	v_fma_f32 v18, -v14, v16, v15
	v_fmac_f32_e32 v16, v18, v17
	v_fma_f32 v14, -v14, v16, v15
	v_div_scale_f32 v15, s[26:27], v20, v20, v100
	v_rcp_f32_e32 v18, v15
	s_or_b32 s21, s20, 12
	v_div_fmas_f32 v14, v14, v17, v16
	s_min_i32 s21, s21, s60
	v_fma_f32 v16, -v15, v18, 1.0
	v_fmac_f32_e32 v18, v16, v18
	v_div_scale_f32 v16, vcc, v100, v20, v100
	v_cvt_f32_i32_e32 v21, s21
	v_mul_f32_e32 v17, v16, v18
	v_div_fixup_f32 v14, v14, v19, v103
	v_fma_f32 v19, -v15, v17, v16
	v_fmac_f32_e32 v17, v19, v18
	v_fma_f32 v15, -v15, v17, v16
	v_div_scale_f32 v16, s[26:27], v21, v21, v101
	v_rcp_f32_e32 v19, v16
	s_or_b32 s21, s20, 13
	v_div_fmas_f32 v15, v15, v18, v17
	s_min_i32 s21, s21, s60
	v_fma_f32 v17, -v16, v19, 1.0
	v_fmac_f32_e32 v19, v17, v19
	v_div_scale_f32 v17, vcc, v101, v21, v101
	v_cvt_f32_i32_e32 v22, s21
	v_mul_f32_e32 v18, v17, v19
	v_div_fixup_f32 v15, v15, v20, v100
	v_fma_f32 v20, -v16, v18, v17
	v_fmac_f32_e32 v18, v20, v19
	v_fma_f32 v16, -v16, v18, v17
	v_div_scale_f32 v17, s[26:27], v22, v22, v98
	v_rcp_f32_e32 v20, v17
	s_or_b32 s21, s20, 14
	v_div_fmas_f32 v16, v16, v19, v18
	s_min_i32 s21, s21, s60
	v_fma_f32 v18, -v17, v20, 1.0
	v_fmac_f32_e32 v20, v18, v20
	v_div_scale_f32 v18, vcc, v98, v22, v98
	v_cvt_f32_i32_e32 v23, s21
	v_mul_f32_e32 v19, v18, v20
	v_div_fixup_f32 v16, v16, v21, v101
	v_fma_f32 v21, -v17, v19, v18
; template <int MODE>
; __device__ __forceinline__ void poolconv_wave(const Ctx& C, int l, int ch, int g, int lane, float* PL) {
;     ...
;     for (int i = 0; i < 16; ++i) { const int pos = pos0 + t0 + i; p[i] = s[15 + i] / (float)min(pos + 1, wnd) - a[i]; acc[i] = 0.f; }
;     const float* wp = C.in[13] + ((size_t)l * 4 + g) * 4096 + lane;
; #pragma unroll
;     for (int i = 0; i < 16; ++i) PL[i * 64 + lane] = p[i];
;     asm volatile("s_waitcnt lgkmcnt(0)" ::: "memory");
; #pragma unroll 2
;     for (int k4 = 0; k4 < 16; ++k4) {
;         const float w0 = wp[(4 * k4 + 0) * 64], w1 = wp[(4 * k4 + 1) * 64], w2 = wp[(4 * k4 + 2) * 64], w3 = wp[(4 * k4 + 3) * 64];
; #pragma unroll
;         for (int i = 0; i < 16; ++i) { const f32x4 pv = *(const f32x4*)(PL + i * 64 + 4 * k4); acc[i] += pv[0] * w0 + pv[1] * w1 + pv[2] * w2 + pv[3] * w3; }
	v_fmac_f32_e32 v19, v21, v20
	v_fma_f32 v17, -v17, v19, v18
	v_div_scale_f32 v18, s[26:27], v23, v23, v99
	v_rcp_f32_e32 v21, v18
	s_or_b32 s21, s20, 15
	v_div_fmas_f32 v17, v17, v20, v19
	s_min_i32 s21, s21, s60
	v_fma_f32 v19, -v18, v21, 1.0
	v_fmac_f32_e32 v21, v19, v21
	v_div_scale_f32 v19, vcc, v99, v23, v99
	v_cvt_f32_i32_e32 v24, s21
	v_mul_f32_e32 v20, v19, v21
	v_div_fixup_f32 v17, v17, v22, v98
	v_fma_f32 v22, -v18, v20, v19
	v_fmac_f32_e32 v20, v22, v21
	v_fma_f32 v18, -v18, v20, v19
	v_div_scale_f32 v19, s[26:27], v24, v24, v2
	v_rcp_f32_e32 v22, v19
	s_add_i32 s20, s20, 16
	v_div_fmas_f32 v18, v18, v21, v20
	s_min_i32 s20, s20, s60
	v_fma_f32 v20, -v19, v22, 1.0
	v_fmac_f32_e32 v22, v20, v22
	v_div_scale_f32 v20, vcc, v2, v24, v2
	v_cvt_f32_i32_e32 v25, s20
	v_mul_f32_e32 v21, v20, v22
	v_div_fixup_f32 v18, v18, v23, v99
	v_fma_f32 v23, -v19, v21, v20
	v_fmac_f32_e32 v21, v23, v22
	v_fma_f32 v19, -v19, v21, v20
	v_div_scale_f32 v20, s[20:21], v25, v25, v3
	v_rcp_f32_e32 v23, v20
	v_div_fmas_f32 v19, v19, v22, v21
	v_div_fixup_f32 v2, v19, v24, v2
	v_sub_f32_e32 v5, v5, v31
	v_fma_f32 v19, -v20, v23, 1.0
	v_fmac_f32_e32 v23, v19, v23
	v_div_scale_f32 v19, vcc, v3, v25, v3
	v_mul_f32_e32 v21, v19, v23
	v_fma_f32 v22, -v20, v21, v19
	v_fmac_f32_e32 v21, v22, v23
	v_fma_f32 v19, -v20, v21, v19
	v_div_fmas_f32 v19, v19, v23, v21
	v_div_fixup_f32 v3, v19, v25, v3
	v_sub_f32_e32 v7, v7, v96
	v_sub_f32_e32 v8, v8, v92
	v_sub_f32_e32 v9, v9, v94
	v_sub_f32_e32 v10, v10, v93
	v_sub_f32_e32 v11, v11, v90
	v_sub_f32_e32 v12, v12, v86
	v_sub_f32_e32 v13, v13, v88
	v_sub_f32_e32 v14, v14, v87
	v_sub_f32_e32 v15, v15, v6
	v_sub_f32_e32 v16, v16, v84
	v_sub_f32_e32 v17, v17, v0
	v_sub_f32_e32 v18, v18, v85
	v_sub_f32_e32 v2, v2, v82
	v_sub_f32_e32 v3, v3, v83
	ds_write2st64_b32 v117, v4, v5 offset1:1
	ds_write2st64_b32 v117, v7, v8 offset0:2 offset1:3
	ds_write2st64_b32 v117, v9, v10 offset0:4 offset1:5
	ds_write2st64_b32 v117, v11, v12 offset0:6 offset1:7
	ds_write2st64_b32 v117, v13, v14 offset0:8 offset1:9
	ds_write2st64_b32 v117, v15, v16 offset0:10 offset1:11
	ds_write2st64_b32 v117, v17, v18 offset0:12 offset1:13
	ds_write2st64_b32 v117, v2, v3 offset0:14 offset1:15
	s_waitcnt lgkmcnt(0)
	s_waitcnt vmcnt(0)
	v_mov_b32_e32 v7, v116
	ds_read_b128 v[2:5], v7
	ds_read_b128 v[24:27], v7 offset:16
	ds_read_b128 v[98:101], v7 offset:32
	s_waitcnt lgkmcnt(2)
	v_mul_f32_e32 v8, v2, v146
	v_mul_f32_e32 v28, v3, v147
	v_fmac_f32_e32 v8, v4, v148
	v_fmac_f32_e32 v28, v5, v149
	ds_read_b128 v[2:5], v7 offset:48
	s_waitcnt lgkmcnt(2)
	v_fmac_f32_e32 v8, v24, v150
	v_fmac_f32_e32 v28, v25, v151
	v_fmac_f32_e32 v8, v26, v152
	v_fmac_f32_e32 v28, v27, v153
	ds_read_b128 v[24:27], v7 offset:64
	s_waitcnt lgkmcnt(2)
	v_fmac_f32_e32 v8, v98, v154
	v_fmac_f32_e32 v28, v99, v155
	v_fmac_f32_e32 v8, v100, v156
	v_fmac_f32_e32 v28, v101, v157
	ds_read_b128 v[98:101], v7 offset:80
	s_waitcnt lgkmcnt(2)
	v_fmac_f32_e32 v8, v2, v158
	v_fmac_f32_e32 v28, v3, v159
	v_fmac_f32_e32 v8, v4, v160
	v_fmac_f32_e32 v28, v5, v161
	ds_read_b128 v[2:5], v7 offset:96
	s_waitcnt lgkmcnt(2)
	v_fmac_f32_e32 v8, v24, v162
	v_fmac_f32_e32 v28, v25, v163
	v_fmac_f32_e32 v8, v26, v164
	v_fmac_f32_e32 v28, v27, v165
	ds_read_b128 v[24:27], v7 offset:112
	s_waitcnt lgkmcnt(2)
	v_fmac_f32_e32 v8, v98, v184
	v_fmac_f32_e32 v28, v99, v185
	v_fmac_f32_e32 v8, v100, v186
	v_fmac_f32_e32 v28, v101, v187
	ds_read_b128 v[98:101], v7 offset:128
	s_waitcnt lgkmcnt(2)
	v_fmac_f32_e32 v8, v2, v188
	v_fmac_f32_e32 v28, v3, v189
	v_fmac_f32_e32 v8, v4, v190
	v_fmac_f32_e32 v28, v5, v191
	ds_read_b128 v[2:5], v7 offset:144
	s_waitcnt lgkmcnt(2)
	v_fmac_f32_e32 v8, v24, v192
	v_fmac_f32_e32 v28, v25, v193
	v_fmac_f32_e32 v8, v26, v196
	v_fmac_f32_e32 v28, v27, v197
	ds_read_b128 v[24:27], v7 offset:160
	s_waitcnt lgkmcnt(2)
	v_fmac_f32_e32 v8, v98, v198
	v_fmac_f32_e32 v28, v99, v199
	v_fmac_f32_e32 v8, v100, v200
	v_fmac_f32_e32 v28, v101, v201
	ds_read_b128 v[98:101], v7 offset:176
	s_waitcnt lgkmcnt(2)
	v_fmac_f32_e32 v8, v2, v202
	v_fmac_f32_e32 v28, v3, v203
	v_fmac_f32_e32 v8, v4, v204
	v_fmac_f32_e32 v28, v5, v205
	ds_read_b128 v[2:5], v7 offset:192
	s_waitcnt lgkmcnt(2)
	v_fmac_f32_e32 v8, v24, v206
	v_fmac_f32_e32 v28, v25, v207
	v_fmac_f32_e32 v8, v26, v208
	v_fmac_f32_e32 v28, v27, v209
	ds_read_b128 v[24:27], v7 offset:208
	s_waitcnt lgkmcnt(2)
	v_fmac_f32_e32 v8, v98, v210
	v_fmac_f32_e32 v28, v99, v211
	v_fmac_f32_e32 v8, v100, v212
	v_fmac_f32_e32 v28, v101, v213
	ds_read_b128 v[98:101], v7 offset:224
	s_waitcnt lgkmcnt(2)
	v_fmac_f32_e32 v8, v2, v214
	v_fmac_f32_e32 v28, v3, v215
	v_fmac_f32_e32 v8, v4, v216
	v_fmac_f32_e32 v28, v5, v217
	ds_read_b128 v[2:5], v7 offset:240
	s_waitcnt lgkmcnt(2)
	v_fmac_f32_e32 v8, v24, v218
	v_fmac_f32_e32 v28, v25, v219
	v_fmac_f32_e32 v8, v26, v220
	v_fmac_f32_e32 v28, v27, v221
	ds_read_b128 v[24:27], v7 offset:256
	s_waitcnt lgkmcnt(2)
	v_fmac_f32_e32 v8, v98, v222
	v_fmac_f32_e32 v28, v99, v223
	v_fmac_f32_e32 v8, v100, v224
	v_fmac_f32_e32 v28, v101, v225
	ds_read_b128 v[98:101], v7 offset:272
	s_waitcnt lgkmcnt(2)
	v_fmac_f32_e32 v8, v2, v226
	v_fmac_f32_e32 v28, v3, v227
	v_fmac_f32_e32 v8, v4, v228
	v_fmac_f32_e32 v28, v5, v229
	v_add_f32_e32 v8, v8, v28
	ds_read_b128 v[2:5], v7 offset:288
	s_waitcnt lgkmcnt(2)
	v_mul_f32_e32 v9, v24, v146
	v_mul_f32_e32 v30, v25, v147
	v_fmac_f32_e32 v9, v26, v148
	v_fmac_f32_e32 v30, v27, v149
	ds_read_b128 v[24:27], v7 offset:304
	s_waitcnt lgkmcnt(2)
	v_fmac_f32_e32 v9, v98, v150
	v_fmac_f32_e32 v30, v99, v151
	v_fmac_f32_e32 v9, v100, v152
	v_fmac_f32_e32 v30, v101, v153
	ds_read_b128 v[98:101], v7 offset:320
	s_waitcnt lgkmcnt(2)
; template <int MODE>
; __device__ __forceinline__ void poolconv_wave(const Ctx& C, int l, int ch, int g, int lane, float* PL) {
;     ...
; #pragma unroll 2
;     for (int k4 = 0; k4 < 16; ++k4) {
;         const float w0 = wp[(4 * k4 + 0) * 64], w1 = wp[(4 * k4 + 1) * 64], w2 = wp[(4 * k4 + 2) * 64], w3 = wp[(4 * k4 + 3) * 64];
; #pragma unroll
;         for (int i = 0; i < 16; ++i) { const f32x4 pv = *(const f32x4*)(PL + i * 64 + 4 * k4); acc[i] += pv[0] * w0 + pv[1] * w1 + pv[2] * w2 + pv[3] * w3; }
;     }
	v_fmac_f32_e32 v9, v2, v154
	v_fmac_f32_e32 v30, v3, v155
	v_fmac_f32_e32 v9, v4, v156
	v_fmac_f32_e32 v30, v5, v157
	ds_read_b128 v[2:5], v7 offset:336
	s_waitcnt lgkmcnt(2)
	v_fmac_f32_e32 v9, v24, v158
	v_fmac_f32_e32 v30, v25, v159
	v_fmac_f32_e32 v9, v26, v160
	v_fmac_f32_e32 v30, v27, v161
	ds_read_b128 v[24:27], v7 offset:352
	s_waitcnt lgkmcnt(2)
	v_fmac_f32_e32 v9, v98, v162
	v_fmac_f32_e32 v30, v99, v163
	v_fmac_f32_e32 v9, v100, v164
	v_fmac_f32_e32 v30, v101, v165
	ds_read_b128 v[98:101], v7 offset:368
	s_waitcnt lgkmcnt(2)
	v_fmac_f32_e32 v9, v2, v184
	v_fmac_f32_e32 v30, v3, v185
	v_fmac_f32_e32 v9, v4, v186
	v_fmac_f32_e32 v30, v5, v187
	ds_read_b128 v[2:5], v7 offset:384
	s_waitcnt lgkmcnt(2)
	v_fmac_f32_e32 v9, v24, v188
	v_fmac_f32_e32 v30, v25, v189
	v_fmac_f32_e32 v9, v26, v190
	v_fmac_f32_e32 v30, v27, v191
	ds_read_b128 v[24:27], v7 offset:400
	s_waitcnt lgkmcnt(2)
	v_fmac_f32_e32 v9, v98, v192
	v_fmac_f32_e32 v30, v99, v193
	v_fmac_f32_e32 v9, v100, v196
	v_fmac_f32_e32 v30, v101, v197
	ds_read_b128 v[98:101], v7 offset:416
	s_waitcnt lgkmcnt(2)
	v_fmac_f32_e32 v9, v2, v198
	v_fmac_f32_e32 v30, v3, v199
	v_fmac_f32_e32 v9, v4, v200
	v_fmac_f32_e32 v30, v5, v201
	ds_read_b128 v[2:5], v7 offset:432
	s_waitcnt lgkmcnt(2)
	v_fmac_f32_e32 v9, v24, v202
	v_fmac_f32_e32 v30, v25, v203
	v_fmac_f32_e32 v9, v26, v204
	v_fmac_f32_e32 v30, v27, v205
	ds_read_b128 v[24:27], v7 offset:448
	s_waitcnt lgkmcnt(2)
	v_fmac_f32_e32 v9, v98, v206
	v_fmac_f32_e32 v30, v99, v207
	v_fmac_f32_e32 v9, v100, v208
	v_fmac_f32_e32 v30, v101, v209
	ds_read_b128 v[98:101], v7 offset:464
	s_waitcnt lgkmcnt(2)
	v_fmac_f32_e32 v9, v2, v210
	v_fmac_f32_e32 v30, v3, v211
	v_fmac_f32_e32 v9, v4, v212
	v_fmac_f32_e32 v30, v5, v213
	ds_read_b128 v[2:5], v7 offset:480
	s_waitcnt lgkmcnt(2)
	v_fmac_f32_e32 v9, v24, v214
	v_fmac_f32_e32 v30, v25, v215
	v_fmac_f32_e32 v9, v26, v216
	v_fmac_f32_e32 v30, v27, v217
	ds_read_b128 v[24:27], v7 offset:496
	s_waitcnt lgkmcnt(2)
	v_fmac_f32_e32 v9, v98, v218
	v_fmac_f32_e32 v30, v99, v219
	v_fmac_f32_e32 v9, v100, v220
	v_fmac_f32_e32 v30, v101, v221
	ds_read_b128 v[98:101], v7 offset:512
	s_waitcnt lgkmcnt(2)
	v_fmac_f32_e32 v9, v2, v222
	v_fmac_f32_e32 v30, v3, v223
	v_fmac_f32_e32 v9, v4, v224
	v_fmac_f32_e32 v30, v5, v225
	ds_read_b128 v[2:5], v7 offset:528
	s_waitcnt lgkmcnt(2)
	v_fmac_f32_e32 v9, v24, v226
	v_fmac_f32_e32 v30, v25, v227
	v_fmac_f32_e32 v9, v26, v228
	v_fmac_f32_e32 v30, v27, v229
	v_add_f32_e32 v9, v9, v30
	ds_read_b128 v[24:27], v7 offset:544
	s_waitcnt lgkmcnt(2)
	v_mul_f32_e32 v10, v98, v146
	v_mul_f32_e32 v28, v99, v147
	v_fmac_f32_e32 v10, v100, v148
	v_fmac_f32_e32 v28, v101, v149
	ds_read_b128 v[98:101], v7 offset:560
	s_waitcnt lgkmcnt(2)
	v_fmac_f32_e32 v10, v2, v150
	v_fmac_f32_e32 v28, v3, v151
	v_fmac_f32_e32 v10, v4, v152
	v_fmac_f32_e32 v28, v5, v153
	ds_read_b128 v[2:5], v7 offset:576
	s_waitcnt lgkmcnt(2)
	v_fmac_f32_e32 v10, v24, v154
	v_fmac_f32_e32 v28, v25, v155
	v_fmac_f32_e32 v10, v26, v156
	v_fmac_f32_e32 v28, v27, v157
	ds_read_b128 v[24:27], v7 offset:592
	s_waitcnt lgkmcnt(2)
	v_fmac_f32_e32 v10, v98, v158
	v_fmac_f32_e32 v28, v99, v159
	v_fmac_f32_e32 v10, v100, v160
	v_fmac_f32_e32 v28, v101, v161
	ds_read_b128 v[98:101], v7 offset:608
	s_waitcnt lgkmcnt(2)
	v_fmac_f32_e32 v10, v2, v162
	v_fmac_f32_e32 v28, v3, v163
	v_fmac_f32_e32 v10, v4, v164
	v_fmac_f32_e32 v28, v5, v165
	ds_read_b128 v[2:5], v7 offset:624
	s_waitcnt lgkmcnt(2)
	v_fmac_f32_e32 v10, v24, v184
	v_fmac_f32_e32 v28, v25, v185
	v_fmac_f32_e32 v10, v26, v186
	v_fmac_f32_e32 v28, v27, v187
	ds_read_b128 v[24:27], v7 offset:640
	s_waitcnt lgkmcnt(2)
	v_fmac_f32_e32 v10, v98, v188
	v_fmac_f32_e32 v28, v99, v189
	v_fmac_f32_e32 v10, v100, v190
	v_fmac_f32_e32 v28, v101, v191
	ds_read_b128 v[98:101], v7 offset:656
	s_waitcnt lgkmcnt(2)
	v_fmac_f32_e32 v10, v2, v192
	v_fmac_f32_e32 v28, v3, v193
	v_fmac_f32_e32 v10, v4, v196
	v_fmac_f32_e32 v28, v5, v197
	ds_read_b128 v[2:5], v7 offset:672
	s_waitcnt lgkmcnt(2)
	v_fmac_f32_e32 v10, v24, v198
	v_fmac_f32_e32 v28, v25, v199
	v_fmac_f32_e32 v10, v26, v200
	v_fmac_f32_e32 v28, v27, v201
	ds_read_b128 v[24:27], v7 offset:688
	s_waitcnt lgkmcnt(2)
	v_fmac_f32_e32 v10, v98, v202
	v_fmac_f32_e32 v28, v99, v203
	v_fmac_f32_e32 v10, v100, v204
	v_fmac_f32_e32 v28, v101, v205
	ds_read_b128 v[98:101], v7 offset:704
	s_waitcnt lgkmcnt(2)
	v_fmac_f32_e32 v10, v2, v206
	v_fmac_f32_e32 v28, v3, v207
	v_fmac_f32_e32 v10, v4, v208
	v_fmac_f32_e32 v28, v5, v209
	ds_read_b128 v[2:5], v7 offset:720
	s_waitcnt lgkmcnt(2)
	v_fmac_f32_e32 v10, v24, v210
	v_fmac_f32_e32 v28, v25, v211
	v_fmac_f32_e32 v10, v26, v212
	v_fmac_f32_e32 v28, v27, v213
	ds_read_b128 v[24:27], v7 offset:736
	s_waitcnt lgkmcnt(2)
	v_fmac_f32_e32 v10, v98, v214
	v_fmac_f32_e32 v28, v99, v215
	v_fmac_f32_e32 v10, v100, v216
	v_fmac_f32_e32 v28, v101, v217
	ds_read_b128 v[98:101], v7 offset:752
	s_waitcnt lgkmcnt(2)
	v_fmac_f32_e32 v10, v2, v218
	v_fmac_f32_e32 v28, v3, v219
	v_fmac_f32_e32 v10, v4, v220
	v_fmac_f32_e32 v28, v5, v221
	ds_read_b128 v[2:5], v7 offset:768
	s_waitcnt lgkmcnt(2)
	v_fmac_f32_e32 v10, v24, v222
	v_fmac_f32_e32 v28, v25, v223
	v_fmac_f32_e32 v10, v26, v224
	v_fmac_f32_e32 v28, v27, v225
	ds_read_b128 v[24:27], v7 offset:784
	s_waitcnt lgkmcnt(2)
	v_fmac_f32_e32 v10, v98, v226
	v_fmac_f32_e32 v28, v99, v227
	v_fmac_f32_e32 v10, v100, v228
	v_fmac_f32_e32 v28, v101, v229
	v_add_f32_e32 v10, v10, v28
	ds_read_b128 v[98:101], v7 offset:800
	s_waitcnt lgkmcnt(2)
	v_mul_f32_e32 v11, v2, v146
	v_mul_f32_e32 v30, v3, v147
	v_fmac_f32_e32 v11, v4, v148
	v_fmac_f32_e32 v30, v5, v149
	ds_read_b128 v[2:5], v7 offset:816
	s_waitcnt lgkmcnt(2)
; template <int MODE>
; __device__ __forceinline__ void poolconv_wave(const Ctx& C, int l, int ch, int g, int lane, float* PL) {
;     ...
; #pragma unroll 2
;     for (int k4 = 0; k4 < 16; ++k4) {
;         const float w0 = wp[(4 * k4 + 0) * 64], w1 = wp[(4 * k4 + 1) * 64], w2 = wp[(4 * k4 + 2) * 64], w3 = wp[(4 * k4 + 3) * 64];
; #pragma unroll
;         for (int i = 0; i < 16; ++i) { const f32x4 pv = *(const f32x4*)(PL + i * 64 + 4 * k4); acc[i] += pv[0] * w0 + pv[1] * w1 + pv[2] * w2 + pv[3] * w3; }
;     }
	v_fmac_f32_e32 v11, v24, v150
	v_fmac_f32_e32 v30, v25, v151
	v_fmac_f32_e32 v11, v26, v152
	v_fmac_f32_e32 v30, v27, v153
	ds_read_b128 v[24:27], v7 offset:832
	s_waitcnt lgkmcnt(2)
	v_fmac_f32_e32 v11, v98, v154
	v_fmac_f32_e32 v30, v99, v155
	v_fmac_f32_e32 v11, v100, v156
	v_fmac_f32_e32 v30, v101, v157
	ds_read_b128 v[98:101], v7 offset:848
	s_waitcnt lgkmcnt(2)
	v_fmac_f32_e32 v11, v2, v158
	v_fmac_f32_e32 v30, v3, v159
	v_fmac_f32_e32 v11, v4, v160
	v_fmac_f32_e32 v30, v5, v161
	ds_read_b128 v[2:5], v7 offset:864
	s_waitcnt lgkmcnt(2)
	v_fmac_f32_e32 v11, v24, v162
	v_fmac_f32_e32 v30, v25, v163
	v_fmac_f32_e32 v11, v26, v164
	v_fmac_f32_e32 v30, v27, v165
	ds_read_b128 v[24:27], v7 offset:880
	s_waitcnt lgkmcnt(2)
	v_fmac_f32_e32 v11, v98, v184
	v_fmac_f32_e32 v30, v99, v185
	v_fmac_f32_e32 v11, v100, v186
	v_fmac_f32_e32 v30, v101, v187
	ds_read_b128 v[98:101], v7 offset:896
	s_waitcnt lgkmcnt(2)
	v_fmac_f32_e32 v11, v2, v188
	v_fmac_f32_e32 v30, v3, v189
	v_fmac_f32_e32 v11, v4, v190
	v_fmac_f32_e32 v30, v5, v191
	ds_read_b128 v[2:5], v7 offset:912
	s_waitcnt lgkmcnt(2)
	v_fmac_f32_e32 v11, v24, v192
	v_fmac_f32_e32 v30, v25, v193
	v_fmac_f32_e32 v11, v26, v196
	v_fmac_f32_e32 v30, v27, v197
	ds_read_b128 v[24:27], v7 offset:928
	s_waitcnt lgkmcnt(2)
	v_fmac_f32_e32 v11, v98, v198
	v_fmac_f32_e32 v30, v99, v199
	v_fmac_f32_e32 v11, v100, v200
	v_fmac_f32_e32 v30, v101, v201
	ds_read_b128 v[98:101], v7 offset:944
	s_waitcnt lgkmcnt(2)
	v_fmac_f32_e32 v11, v2, v202
	v_fmac_f32_e32 v30, v3, v203
	v_fmac_f32_e32 v11, v4, v204
	v_fmac_f32_e32 v30, v5, v205
	ds_read_b128 v[2:5], v7 offset:960
	s_waitcnt lgkmcnt(2)
	v_fmac_f32_e32 v11, v24, v206
	v_fmac_f32_e32 v30, v25, v207
	v_fmac_f32_e32 v11, v26, v208
	v_fmac_f32_e32 v30, v27, v209
	ds_read_b128 v[24:27], v7 offset:976
	s_waitcnt lgkmcnt(2)
	v_fmac_f32_e32 v11, v98, v210
	v_fmac_f32_e32 v30, v99, v211
	v_fmac_f32_e32 v11, v100, v212
	v_fmac_f32_e32 v30, v101, v213
	ds_read_b128 v[98:101], v7 offset:992
	s_waitcnt lgkmcnt(2)
	v_fmac_f32_e32 v11, v2, v214
	v_fmac_f32_e32 v30, v3, v215
	v_fmac_f32_e32 v11, v4, v216
	v_fmac_f32_e32 v30, v5, v217
	ds_read_b128 v[2:5], v7 offset:1008
	s_waitcnt lgkmcnt(2)
	v_fmac_f32_e32 v11, v24, v218
	v_fmac_f32_e32 v30, v25, v219
	v_fmac_f32_e32 v11, v26, v220
	v_fmac_f32_e32 v30, v27, v221
	ds_read_b128 v[24:27], v7 offset:1024
	s_waitcnt lgkmcnt(2)
	v_fmac_f32_e32 v11, v98, v222
	v_fmac_f32_e32 v30, v99, v223
	v_fmac_f32_e32 v11, v100, v224
	v_fmac_f32_e32 v30, v101, v225
	ds_read_b128 v[98:101], v7 offset:1040
	s_waitcnt lgkmcnt(2)
	v_fmac_f32_e32 v11, v2, v226
	v_fmac_f32_e32 v30, v3, v227
	v_fmac_f32_e32 v11, v4, v228
	v_fmac_f32_e32 v30, v5, v229
	v_add_f32_e32 v11, v11, v30
	ds_read_b128 v[2:5], v7 offset:1056
	s_waitcnt lgkmcnt(2)
	v_mul_f32_e32 v12, v24, v146
	v_mul_f32_e32 v28, v25, v147
	v_fmac_f32_e32 v12, v26, v148
	v_fmac_f32_e32 v28, v27, v149
	ds_read_b128 v[24:27], v7 offset:1072
	s_waitcnt lgkmcnt(2)
	v_fmac_f32_e32 v12, v98, v150
	v_fmac_f32_e32 v28, v99, v151
	v_fmac_f32_e32 v12, v100, v152
	v_fmac_f32_e32 v28, v101, v153
	ds_read_b128 v[98:101], v7 offset:1088
	s_waitcnt lgkmcnt(2)
	v_fmac_f32_e32 v12, v2, v154
	v_fmac_f32_e32 v28, v3, v155
	v_fmac_f32_e32 v12, v4, v156
	v_fmac_f32_e32 v28, v5, v157
	ds_read_b128 v[2:5], v7 offset:1104
	s_waitcnt lgkmcnt(2)
	v_fmac_f32_e32 v12, v24, v158
	v_fmac_f32_e32 v28, v25, v159
	v_fmac_f32_e32 v12, v26, v160
	v_fmac_f32_e32 v28, v27, v161
	ds_read_b128 v[24:27], v7 offset:1120
	s_waitcnt lgkmcnt(2)
	v_fmac_f32_e32 v12, v98, v162
	v_fmac_f32_e32 v28, v99, v163
	v_fmac_f32_e32 v12, v100, v164
	v_fmac_f32_e32 v28, v101, v165
	ds_read_b128 v[98:101], v7 offset:1136
	s_waitcnt lgkmcnt(2)
	v_fmac_f32_e32 v12, v2, v184
	v_fmac_f32_e32 v28, v3, v185
	v_fmac_f32_e32 v12, v4, v186
	v_fmac_f32_e32 v28, v5, v187
	ds_read_b128 v[2:5], v7 offset:1152
	s_waitcnt lgkmcnt(2)
	v_fmac_f32_e32 v12, v24, v188
	v_fmac_f32_e32 v28, v25, v189
	v_fmac_f32_e32 v12, v26, v190
	v_fmac_f32_e32 v28, v27, v191
	ds_read_b128 v[24:27], v7 offset:1168
	s_waitcnt lgkmcnt(2)
	v_fmac_f32_e32 v12, v98, v192
	v_fmac_f32_e32 v28, v99, v193
	v_fmac_f32_e32 v12, v100, v196
	v_fmac_f32_e32 v28, v101, v197
	ds_read_b128 v[98:101], v7 offset:1184
	s_waitcnt lgkmcnt(2)
	v_fmac_f32_e32 v12, v2, v198
	v_fmac_f32_e32 v28, v3, v199
	v_fmac_f32_e32 v12, v4, v200
	v_fmac_f32_e32 v28, v5, v201
	ds_read_b128 v[2:5], v7 offset:1200
	s_waitcnt lgkmcnt(2)
	v_fmac_f32_e32 v12, v24, v202
	v_fmac_f32_e32 v28, v25, v203
	v_fmac_f32_e32 v12, v26, v204
	v_fmac_f32_e32 v28, v27, v205
	ds_read_b128 v[24:27], v7 offset:1216
	s_waitcnt lgkmcnt(2)
	v_fmac_f32_e32 v12, v98, v206
	v_fmac_f32_e32 v28, v99, v207
	v_fmac_f32_e32 v12, v100, v208
	v_fmac_f32_e32 v28, v101, v209
	ds_read_b128 v[98:101], v7 offset:1232
	s_waitcnt lgkmcnt(2)
	v_fmac_f32_e32 v12, v2, v210
	v_fmac_f32_e32 v28, v3, v211
	v_fmac_f32_e32 v12, v4, v212
	v_fmac_f32_e32 v28, v5, v213
	ds_read_b128 v[2:5], v7 offset:1248
	s_waitcnt lgkmcnt(2)
	v_fmac_f32_e32 v12, v24, v214
	v_fmac_f32_e32 v28, v25, v215
	v_fmac_f32_e32 v12, v26, v216
	v_fmac_f32_e32 v28, v27, v217
	ds_read_b128 v[24:27], v7 offset:1264
	s_waitcnt lgkmcnt(2)
	v_fmac_f32_e32 v12, v98, v218
	v_fmac_f32_e32 v28, v99, v219
	v_fmac_f32_e32 v12, v100, v220
	v_fmac_f32_e32 v28, v101, v221
	ds_read_b128 v[98:101], v7 offset:1280
	s_waitcnt lgkmcnt(2)
	v_fmac_f32_e32 v12, v2, v222
	v_fmac_f32_e32 v28, v3, v223
	v_fmac_f32_e32 v12, v4, v224
	v_fmac_f32_e32 v28, v5, v225
	ds_read_b128 v[2:5], v7 offset:1296
	s_waitcnt lgkmcnt(2)
; template <int MODE>
; __device__ __forceinline__ void poolconv_wave(const Ctx& C, int l, int ch, int g, int lane, float* PL) {
;     ...
; #pragma unroll 2
;     for (int k4 = 0; k4 < 16; ++k4) {
;         const float w0 = wp[(4 * k4 + 0) * 64], w1 = wp[(4 * k4 + 1) * 64], w2 = wp[(4 * k4 + 2) * 64], w3 = wp[(4 * k4 + 3) * 64];
; #pragma unroll
;         for (int i = 0; i < 16; ++i) { const f32x4 pv = *(const f32x4*)(PL + i * 64 + 4 * k4); acc[i] += pv[0] * w0 + pv[1] * w1 + pv[2] * w2 + pv[3] * w3; }
;     }
	v_fmac_f32_e32 v12, v24, v226
	v_fmac_f32_e32 v28, v25, v227
	v_fmac_f32_e32 v12, v26, v228
	v_fmac_f32_e32 v28, v27, v229
	v_add_f32_e32 v12, v12, v28
	ds_read_b128 v[24:27], v7 offset:1312
	s_waitcnt lgkmcnt(2)
	v_mul_f32_e32 v13, v98, v146
	v_mul_f32_e32 v30, v99, v147
	v_fmac_f32_e32 v13, v100, v148
	v_fmac_f32_e32 v30, v101, v149
	ds_read_b128 v[98:101], v7 offset:1328
	s_waitcnt lgkmcnt(2)
	v_fmac_f32_e32 v13, v2, v150
	v_fmac_f32_e32 v30, v3, v151
	v_fmac_f32_e32 v13, v4, v152
	v_fmac_f32_e32 v30, v5, v153
	ds_read_b128 v[2:5], v7 offset:1344
	s_waitcnt lgkmcnt(2)
	v_fmac_f32_e32 v13, v24, v154
	v_fmac_f32_e32 v30, v25, v155
	v_fmac_f32_e32 v13, v26, v156
	v_fmac_f32_e32 v30, v27, v157
	ds_read_b128 v[24:27], v7 offset:1360
	s_waitcnt lgkmcnt(2)
	v_fmac_f32_e32 v13, v98, v158
	v_fmac_f32_e32 v30, v99, v159
	v_fmac_f32_e32 v13, v100, v160
	v_fmac_f32_e32 v30, v101, v161
	ds_read_b128 v[98:101], v7 offset:1376
	s_waitcnt lgkmcnt(2)
	v_fmac_f32_e32 v13, v2, v162
	v_fmac_f32_e32 v30, v3, v163
	v_fmac_f32_e32 v13, v4, v164
	v_fmac_f32_e32 v30, v5, v165
	ds_read_b128 v[2:5], v7 offset:1392
	s_waitcnt lgkmcnt(2)
	v_fmac_f32_e32 v13, v24, v184
	v_fmac_f32_e32 v30, v25, v185
	v_fmac_f32_e32 v13, v26, v186
	v_fmac_f32_e32 v30, v27, v187
	ds_read_b128 v[24:27], v7 offset:1408
	s_waitcnt lgkmcnt(2)
	v_fmac_f32_e32 v13, v98, v188
	v_fmac_f32_e32 v30, v99, v189
	v_fmac_f32_e32 v13, v100, v190
	v_fmac_f32_e32 v30, v101, v191
	ds_read_b128 v[98:101], v7 offset:1424
	s_waitcnt lgkmcnt(2)
	v_fmac_f32_e32 v13, v2, v192
	v_fmac_f32_e32 v30, v3, v193
	v_fmac_f32_e32 v13, v4, v196
	v_fmac_f32_e32 v30, v5, v197
	ds_read_b128 v[2:5], v7 offset:1440
	s_waitcnt lgkmcnt(2)
	v_fmac_f32_e32 v13, v24, v198
	v_fmac_f32_e32 v30, v25, v199
	v_fmac_f32_e32 v13, v26, v200
	v_fmac_f32_e32 v30, v27, v201
	ds_read_b128 v[24:27], v7 offset:1456
	s_waitcnt lgkmcnt(2)
	v_fmac_f32_e32 v13, v98, v202
	v_fmac_f32_e32 v30, v99, v203
	v_fmac_f32_e32 v13, v100, v204
	v_fmac_f32_e32 v30, v101, v205
	ds_read_b128 v[98:101], v7 offset:1472
	s_waitcnt lgkmcnt(2)
	v_fmac_f32_e32 v13, v2, v206
	v_fmac_f32_e32 v30, v3, v207
	v_fmac_f32_e32 v13, v4, v208
	v_fmac_f32_e32 v30, v5, v209
	ds_read_b128 v[2:5], v7 offset:1488
	s_waitcnt lgkmcnt(2)
	v_fmac_f32_e32 v13, v24, v210
	v_fmac_f32_e32 v30, v25, v211
	v_fmac_f32_e32 v13, v26, v212
	v_fmac_f32_e32 v30, v27, v213
	ds_read_b128 v[24:27], v7 offset:1504
	s_waitcnt lgkmcnt(2)
	v_fmac_f32_e32 v13, v98, v214
	v_fmac_f32_e32 v30, v99, v215
	v_fmac_f32_e32 v13, v100, v216
	v_fmac_f32_e32 v30, v101, v217
	ds_read_b128 v[98:101], v7 offset:1520
	s_waitcnt lgkmcnt(2)
	v_fmac_f32_e32 v13, v2, v218
	v_fmac_f32_e32 v30, v3, v219
	v_fmac_f32_e32 v13, v4, v220
	v_fmac_f32_e32 v30, v5, v221
	ds_read_b128 v[2:5], v7 offset:1536
	s_waitcnt lgkmcnt(2)
	v_fmac_f32_e32 v13, v24, v222
	v_fmac_f32_e32 v30, v25, v223
	v_fmac_f32_e32 v13, v26, v224
	v_fmac_f32_e32 v30, v27, v225
	ds_read_b128 v[24:27], v7 offset:1552
	s_waitcnt lgkmcnt(2)
	v_fmac_f32_e32 v13, v98, v226
	v_fmac_f32_e32 v30, v99, v227
	v_fmac_f32_e32 v13, v100, v228
	v_fmac_f32_e32 v30, v101, v229
	v_add_f32_e32 v13, v13, v30
	ds_read_b128 v[98:101], v7 offset:1568
	s_waitcnt lgkmcnt(2)
	v_mul_f32_e32 v14, v2, v146
	v_mul_f32_e32 v28, v3, v147
	v_fmac_f32_e32 v14, v4, v148
	v_fmac_f32_e32 v28, v5, v149
	ds_read_b128 v[2:5], v7 offset:1584
	s_waitcnt lgkmcnt(2)
	v_fmac_f32_e32 v14, v24, v150
	v_fmac_f32_e32 v28, v25, v151
	v_fmac_f32_e32 v14, v26, v152
	v_fmac_f32_e32 v28, v27, v153
	ds_read_b128 v[24:27], v7 offset:1600
	s_waitcnt lgkmcnt(2)
	v_fmac_f32_e32 v14, v98, v154
	v_fmac_f32_e32 v28, v99, v155
	v_fmac_f32_e32 v14, v100, v156
	v_fmac_f32_e32 v28, v101, v157
	ds_read_b128 v[98:101], v7 offset:1616
	s_waitcnt lgkmcnt(2)
	v_fmac_f32_e32 v14, v2, v158
	v_fmac_f32_e32 v28, v3, v159
	v_fmac_f32_e32 v14, v4, v160
	v_fmac_f32_e32 v28, v5, v161
	ds_read_b128 v[2:5], v7 offset:1632
	s_waitcnt lgkmcnt(2)
	v_fmac_f32_e32 v14, v24, v162
	v_fmac_f32_e32 v28, v25, v163
	v_fmac_f32_e32 v14, v26, v164
	v_fmac_f32_e32 v28, v27, v165
	ds_read_b128 v[24:27], v7 offset:1648
	s_waitcnt lgkmcnt(2)
	v_fmac_f32_e32 v14, v98, v184
	v_fmac_f32_e32 v28, v99, v185
	v_fmac_f32_e32 v14, v100, v186
	v_fmac_f32_e32 v28, v101, v187
	ds_read_b128 v[98:101], v7 offset:1664
	s_waitcnt lgkmcnt(2)
	v_fmac_f32_e32 v14, v2, v188
	v_fmac_f32_e32 v28, v3, v189
	v_fmac_f32_e32 v14, v4, v190
	v_fmac_f32_e32 v28, v5, v191
	ds_read_b128 v[2:5], v7 offset:1680
	s_waitcnt lgkmcnt(2)
	v_fmac_f32_e32 v14, v24, v192
	v_fmac_f32_e32 v28, v25, v193
	v_fmac_f32_e32 v14, v26, v196
	v_fmac_f32_e32 v28, v27, v197
	ds_read_b128 v[24:27], v7 offset:1696
	s_waitcnt lgkmcnt(2)
	v_fmac_f32_e32 v14, v98, v198
	v_fmac_f32_e32 v28, v99, v199
	v_fmac_f32_e32 v14, v100, v200
	v_fmac_f32_e32 v28, v101, v201
	ds_read_b128 v[98:101], v7 offset:1712
	s_waitcnt lgkmcnt(2)
	v_fmac_f32_e32 v14, v2, v202
	v_fmac_f32_e32 v28, v3, v203
	v_fmac_f32_e32 v14, v4, v204
	v_fmac_f32_e32 v28, v5, v205
	ds_read_b128 v[2:5], v7 offset:1728
	s_waitcnt lgkmcnt(2)
	v_fmac_f32_e32 v14, v24, v206
	v_fmac_f32_e32 v28, v25, v207
	v_fmac_f32_e32 v14, v26, v208
	v_fmac_f32_e32 v28, v27, v209
	ds_read_b128 v[24:27], v7 offset:1744
	s_waitcnt lgkmcnt(2)
	v_fmac_f32_e32 v14, v98, v210
	v_fmac_f32_e32 v28, v99, v211
	v_fmac_f32_e32 v14, v100, v212
	v_fmac_f32_e32 v28, v101, v213
	ds_read_b128 v[98:101], v7 offset:1760
	s_waitcnt lgkmcnt(2)
	v_fmac_f32_e32 v14, v2, v214
	v_fmac_f32_e32 v28, v3, v215
	v_fmac_f32_e32 v14, v4, v216
	v_fmac_f32_e32 v28, v5, v217
	ds_read_b128 v[2:5], v7 offset:1776
	s_waitcnt lgkmcnt(2)
; template <int MODE>
; __device__ __forceinline__ void poolconv_wave(const Ctx& C, int l, int ch, int g, int lane, float* PL) {
;     ...
; #pragma unroll 2
;     for (int k4 = 0; k4 < 16; ++k4) {
;         const float w0 = wp[(4 * k4 + 0) * 64], w1 = wp[(4 * k4 + 1) * 64], w2 = wp[(4 * k4 + 2) * 64], w3 = wp[(4 * k4 + 3) * 64];
; #pragma unroll
;         for (int i = 0; i < 16; ++i) { const f32x4 pv = *(const f32x4*)(PL + i * 64 + 4 * k4); acc[i] += pv[0] * w0 + pv[1] * w1 + pv[2] * w2 + pv[3] * w3; }
;     }
	v_fmac_f32_e32 v14, v24, v218
	v_fmac_f32_e32 v28, v25, v219
	v_fmac_f32_e32 v14, v26, v220
	v_fmac_f32_e32 v28, v27, v221
	ds_read_b128 v[24:27], v7 offset:1792
	s_waitcnt lgkmcnt(2)
	v_fmac_f32_e32 v14, v98, v222
	v_fmac_f32_e32 v28, v99, v223
	v_fmac_f32_e32 v14, v100, v224
	v_fmac_f32_e32 v28, v101, v225
	ds_read_b128 v[98:101], v7 offset:1808
	s_waitcnt lgkmcnt(2)
	v_fmac_f32_e32 v14, v2, v226
	v_fmac_f32_e32 v28, v3, v227
	v_fmac_f32_e32 v14, v4, v228
	v_fmac_f32_e32 v28, v5, v229
	v_add_f32_e32 v14, v14, v28
	ds_read_b128 v[2:5], v7 offset:1824
	s_waitcnt lgkmcnt(2)
	v_mul_f32_e32 v15, v24, v146
	v_mul_f32_e32 v30, v25, v147
	v_fmac_f32_e32 v15, v26, v148
	v_fmac_f32_e32 v30, v27, v149
	ds_read_b128 v[24:27], v7 offset:1840
	s_waitcnt lgkmcnt(2)
	v_fmac_f32_e32 v15, v98, v150
	v_fmac_f32_e32 v30, v99, v151
	v_fmac_f32_e32 v15, v100, v152
	v_fmac_f32_e32 v30, v101, v153
	ds_read_b128 v[98:101], v7 offset:1856
	s_waitcnt lgkmcnt(2)
	v_fmac_f32_e32 v15, v2, v154
	v_fmac_f32_e32 v30, v3, v155
	v_fmac_f32_e32 v15, v4, v156
	v_fmac_f32_e32 v30, v5, v157
	ds_read_b128 v[2:5], v7 offset:1872
	s_waitcnt lgkmcnt(2)
	v_fmac_f32_e32 v15, v24, v158
	v_fmac_f32_e32 v30, v25, v159
	v_fmac_f32_e32 v15, v26, v160
	v_fmac_f32_e32 v30, v27, v161
	ds_read_b128 v[24:27], v7 offset:1888
	s_waitcnt lgkmcnt(2)
	v_fmac_f32_e32 v15, v98, v162
	v_fmac_f32_e32 v30, v99, v163
	v_fmac_f32_e32 v15, v100, v164
	v_fmac_f32_e32 v30, v101, v165
	ds_read_b128 v[98:101], v7 offset:1904
	s_waitcnt lgkmcnt(2)
	v_fmac_f32_e32 v15, v2, v184
	v_fmac_f32_e32 v30, v3, v185
	v_fmac_f32_e32 v15, v4, v186
	v_fmac_f32_e32 v30, v5, v187
	ds_read_b128 v[2:5], v7 offset:1920
	s_waitcnt lgkmcnt(2)
	v_fmac_f32_e32 v15, v24, v188
	v_fmac_f32_e32 v30, v25, v189
	v_fmac_f32_e32 v15, v26, v190
	v_fmac_f32_e32 v30, v27, v191
	ds_read_b128 v[24:27], v7 offset:1936
	s_waitcnt lgkmcnt(2)
	v_fmac_f32_e32 v15, v98, v192
	v_fmac_f32_e32 v30, v99, v193
	v_fmac_f32_e32 v15, v100, v196
	v_fmac_f32_e32 v30, v101, v197
	ds_read_b128 v[98:101], v7 offset:1952
	s_waitcnt lgkmcnt(2)
	v_fmac_f32_e32 v15, v2, v198
	v_fmac_f32_e32 v30, v3, v199
	v_fmac_f32_e32 v15, v4, v200
	v_fmac_f32_e32 v30, v5, v201
	ds_read_b128 v[2:5], v7 offset:1968
	s_waitcnt lgkmcnt(2)
	v_fmac_f32_e32 v15, v24, v202
	v_fmac_f32_e32 v30, v25, v203
	v_fmac_f32_e32 v15, v26, v204
	v_fmac_f32_e32 v30, v27, v205
	ds_read_b128 v[24:27], v7 offset:1984
	s_waitcnt lgkmcnt(2)
	v_fmac_f32_e32 v15, v98, v206
	v_fmac_f32_e32 v30, v99, v207
	v_fmac_f32_e32 v15, v100, v208
	v_fmac_f32_e32 v30, v101, v209
	ds_read_b128 v[98:101], v7 offset:2000
	s_waitcnt lgkmcnt(2)
	v_fmac_f32_e32 v15, v2, v210
	v_fmac_f32_e32 v30, v3, v211
	v_fmac_f32_e32 v15, v4, v212
	v_fmac_f32_e32 v30, v5, v213
	ds_read_b128 v[2:5], v7 offset:2016
	s_waitcnt lgkmcnt(2)
	v_fmac_f32_e32 v15, v24, v214
	v_fmac_f32_e32 v30, v25, v215
	v_fmac_f32_e32 v15, v26, v216
	v_fmac_f32_e32 v30, v27, v217
	ds_read_b128 v[24:27], v7 offset:2032
	s_waitcnt lgkmcnt(2)
	v_fmac_f32_e32 v15, v98, v218
	v_fmac_f32_e32 v30, v99, v219
	v_fmac_f32_e32 v15, v100, v220
	v_fmac_f32_e32 v30, v101, v221
	ds_read_b128 v[98:101], v7 offset:2048
	s_waitcnt lgkmcnt(2)
	v_fmac_f32_e32 v15, v2, v222
	v_fmac_f32_e32 v30, v3, v223
	v_fmac_f32_e32 v15, v4, v224
	v_fmac_f32_e32 v30, v5, v225
	ds_read_b128 v[2:5], v7 offset:2064
	s_waitcnt lgkmcnt(2)
	v_fmac_f32_e32 v15, v24, v226
	v_fmac_f32_e32 v30, v25, v227
	v_fmac_f32_e32 v15, v26, v228
	v_fmac_f32_e32 v30, v27, v229
	v_add_f32_e32 v15, v15, v30
	ds_read_b128 v[24:27], v7 offset:2080
	s_waitcnt lgkmcnt(2)
	v_mul_f32_e32 v16, v98, v146
	v_mul_f32_e32 v28, v99, v147
	v_fmac_f32_e32 v16, v100, v148
	v_fmac_f32_e32 v28, v101, v149
	ds_read_b128 v[98:101], v7 offset:2096
	s_waitcnt lgkmcnt(2)
	v_fmac_f32_e32 v16, v2, v150
	v_fmac_f32_e32 v28, v3, v151
	v_fmac_f32_e32 v16, v4, v152
	v_fmac_f32_e32 v28, v5, v153
	ds_read_b128 v[2:5], v7 offset:2112
	s_waitcnt lgkmcnt(2)
	v_fmac_f32_e32 v16, v24, v154
	v_fmac_f32_e32 v28, v25, v155
	v_fmac_f32_e32 v16, v26, v156
	v_fmac_f32_e32 v28, v27, v157
	ds_read_b128 v[24:27], v7 offset:2128
	s_waitcnt lgkmcnt(2)
	v_fmac_f32_e32 v16, v98, v158
	v_fmac_f32_e32 v28, v99, v159
	v_fmac_f32_e32 v16, v100, v160
	v_fmac_f32_e32 v28, v101, v161
	ds_read_b128 v[98:101], v7 offset:2144
	s_waitcnt lgkmcnt(2)
	v_fmac_f32_e32 v16, v2, v162
	v_fmac_f32_e32 v28, v3, v163
	v_fmac_f32_e32 v16, v4, v164
	v_fmac_f32_e32 v28, v5, v165
	ds_read_b128 v[2:5], v7 offset:2160
	s_waitcnt lgkmcnt(2)
	v_fmac_f32_e32 v16, v24, v184
	v_fmac_f32_e32 v28, v25, v185
	v_fmac_f32_e32 v16, v26, v186
	v_fmac_f32_e32 v28, v27, v187
	ds_read_b128 v[24:27], v7 offset:2176
	s_waitcnt lgkmcnt(2)
	v_fmac_f32_e32 v16, v98, v188
	v_fmac_f32_e32 v28, v99, v189
	v_fmac_f32_e32 v16, v100, v190
	v_fmac_f32_e32 v28, v101, v191
	ds_read_b128 v[98:101], v7 offset:2192
	s_waitcnt lgkmcnt(2)
	v_fmac_f32_e32 v16, v2, v192
	v_fmac_f32_e32 v28, v3, v193
	v_fmac_f32_e32 v16, v4, v196
	v_fmac_f32_e32 v28, v5, v197
	ds_read_b128 v[2:5], v7 offset:2208
	s_waitcnt lgkmcnt(2)
	v_fmac_f32_e32 v16, v24, v198
	v_fmac_f32_e32 v28, v25, v199
	v_fmac_f32_e32 v16, v26, v200
	v_fmac_f32_e32 v28, v27, v201
	ds_read_b128 v[24:27], v7 offset:2224
	s_waitcnt lgkmcnt(2)
	v_fmac_f32_e32 v16, v98, v202
	v_fmac_f32_e32 v28, v99, v203
	v_fmac_f32_e32 v16, v100, v204
	v_fmac_f32_e32 v28, v101, v205
	ds_read_b128 v[98:101], v7 offset:2240
	s_waitcnt lgkmcnt(2)
	v_fmac_f32_e32 v16, v2, v206
	v_fmac_f32_e32 v28, v3, v207
	v_fmac_f32_e32 v16, v4, v208
	v_fmac_f32_e32 v28, v5, v209
	ds_read_b128 v[2:5], v7 offset:2256
	s_waitcnt lgkmcnt(2)
; template <int MODE>
; __device__ __forceinline__ void poolconv_wave(const Ctx& C, int l, int ch, int g, int lane, float* PL) {
;     ...
; #pragma unroll 2
;     for (int k4 = 0; k4 < 16; ++k4) {
;         const float w0 = wp[(4 * k4 + 0) * 64], w1 = wp[(4 * k4 + 1) * 64], w2 = wp[(4 * k4 + 2) * 64], w3 = wp[(4 * k4 + 3) * 64];
; #pragma unroll
;         for (int i = 0; i < 16; ++i) { const f32x4 pv = *(const f32x4*)(PL + i * 64 + 4 * k4); acc[i] += pv[0] * w0 + pv[1] * w1 + pv[2] * w2 + pv[3] * w3; }
;     }
	v_fmac_f32_e32 v16, v24, v210
	v_fmac_f32_e32 v28, v25, v211
	v_fmac_f32_e32 v16, v26, v212
	v_fmac_f32_e32 v28, v27, v213
	ds_read_b128 v[24:27], v7 offset:2272
	s_waitcnt lgkmcnt(2)
	v_fmac_f32_e32 v16, v98, v214
	v_fmac_f32_e32 v28, v99, v215
	v_fmac_f32_e32 v16, v100, v216
	v_fmac_f32_e32 v28, v101, v217
	ds_read_b128 v[98:101], v7 offset:2288
	s_waitcnt lgkmcnt(2)
	v_fmac_f32_e32 v16, v2, v218
	v_fmac_f32_e32 v28, v3, v219
	v_fmac_f32_e32 v16, v4, v220
	v_fmac_f32_e32 v28, v5, v221
	ds_read_b128 v[2:5], v7 offset:2304
	s_waitcnt lgkmcnt(2)
	v_fmac_f32_e32 v16, v24, v222
	v_fmac_f32_e32 v28, v25, v223
	v_fmac_f32_e32 v16, v26, v224
	v_fmac_f32_e32 v28, v27, v225
	ds_read_b128 v[24:27], v7 offset:2320
	s_waitcnt lgkmcnt(2)
	v_fmac_f32_e32 v16, v98, v226
	v_fmac_f32_e32 v28, v99, v227
	v_fmac_f32_e32 v16, v100, v228
	v_fmac_f32_e32 v28, v101, v229
	v_add_f32_e32 v16, v16, v28
	ds_read_b128 v[98:101], v7 offset:2336
	s_waitcnt lgkmcnt(2)
	v_mul_f32_e32 v17, v2, v146
	v_mul_f32_e32 v30, v3, v147
	v_fmac_f32_e32 v17, v4, v148
	v_fmac_f32_e32 v30, v5, v149
	ds_read_b128 v[2:5], v7 offset:2352
	s_waitcnt lgkmcnt(2)
	v_fmac_f32_e32 v17, v24, v150
	v_fmac_f32_e32 v30, v25, v151
	v_fmac_f32_e32 v17, v26, v152
	v_fmac_f32_e32 v30, v27, v153
	ds_read_b128 v[24:27], v7 offset:2368
	s_waitcnt lgkmcnt(2)
	v_fmac_f32_e32 v17, v98, v154
	v_fmac_f32_e32 v30, v99, v155
	v_fmac_f32_e32 v17, v100, v156
	v_fmac_f32_e32 v30, v101, v157
	ds_read_b128 v[98:101], v7 offset:2384
	s_waitcnt lgkmcnt(2)
	v_fmac_f32_e32 v17, v2, v158
	v_fmac_f32_e32 v30, v3, v159
	v_fmac_f32_e32 v17, v4, v160
	v_fmac_f32_e32 v30, v5, v161
	ds_read_b128 v[2:5], v7 offset:2400
	s_waitcnt lgkmcnt(2)
	v_fmac_f32_e32 v17, v24, v162
	v_fmac_f32_e32 v30, v25, v163
	v_fmac_f32_e32 v17, v26, v164
	v_fmac_f32_e32 v30, v27, v165
	ds_read_b128 v[24:27], v7 offset:2416
	s_waitcnt lgkmcnt(2)
	v_fmac_f32_e32 v17, v98, v184
	v_fmac_f32_e32 v30, v99, v185
	v_fmac_f32_e32 v17, v100, v186
	v_fmac_f32_e32 v30, v101, v187
	ds_read_b128 v[98:101], v7 offset:2432
	s_waitcnt lgkmcnt(2)
	v_fmac_f32_e32 v17, v2, v188
	v_fmac_f32_e32 v30, v3, v189
	v_fmac_f32_e32 v17, v4, v190
	v_fmac_f32_e32 v30, v5, v191
	ds_read_b128 v[2:5], v7 offset:2448
	s_waitcnt lgkmcnt(2)
	v_fmac_f32_e32 v17, v24, v192
	v_fmac_f32_e32 v30, v25, v193
	v_fmac_f32_e32 v17, v26, v196
	v_fmac_f32_e32 v30, v27, v197
	ds_read_b128 v[24:27], v7 offset:2464
	s_waitcnt lgkmcnt(2)
	v_fmac_f32_e32 v17, v98, v198
	v_fmac_f32_e32 v30, v99, v199
	v_fmac_f32_e32 v17, v100, v200
	v_fmac_f32_e32 v30, v101, v201
	ds_read_b128 v[98:101], v7 offset:2480
	s_waitcnt lgkmcnt(2)
	v_fmac_f32_e32 v17, v2, v202
	v_fmac_f32_e32 v30, v3, v203
	v_fmac_f32_e32 v17, v4, v204
	v_fmac_f32_e32 v30, v5, v205
	ds_read_b128 v[2:5], v7 offset:2496
	s_waitcnt lgkmcnt(2)
	v_fmac_f32_e32 v17, v24, v206
	v_fmac_f32_e32 v30, v25, v207
	v_fmac_f32_e32 v17, v26, v208
	v_fmac_f32_e32 v30, v27, v209
	ds_read_b128 v[24:27], v7 offset:2512
	s_waitcnt lgkmcnt(2)
	v_fmac_f32_e32 v17, v98, v210
	v_fmac_f32_e32 v30, v99, v211
	v_fmac_f32_e32 v17, v100, v212
	v_fmac_f32_e32 v30, v101, v213
	ds_read_b128 v[98:101], v7 offset:2528
	s_waitcnt lgkmcnt(2)
	v_fmac_f32_e32 v17, v2, v214
	v_fmac_f32_e32 v30, v3, v215
	v_fmac_f32_e32 v17, v4, v216
	v_fmac_f32_e32 v30, v5, v217
	ds_read_b128 v[2:5], v7 offset:2544
	s_waitcnt lgkmcnt(2)
	v_fmac_f32_e32 v17, v24, v218
	v_fmac_f32_e32 v30, v25, v219
	v_fmac_f32_e32 v17, v26, v220
	v_fmac_f32_e32 v30, v27, v221
	ds_read_b128 v[24:27], v7 offset:2560
	s_waitcnt lgkmcnt(2)
	v_fmac_f32_e32 v17, v98, v222
	v_fmac_f32_e32 v30, v99, v223
	v_fmac_f32_e32 v17, v100, v224
	v_fmac_f32_e32 v30, v101, v225
	ds_read_b128 v[98:101], v7 offset:2576
	s_waitcnt lgkmcnt(2)
	v_fmac_f32_e32 v17, v2, v226
	v_fmac_f32_e32 v30, v3, v227
	v_fmac_f32_e32 v17, v4, v228
	v_fmac_f32_e32 v30, v5, v229
	v_add_f32_e32 v17, v17, v30
	ds_read_b128 v[2:5], v7 offset:2592
	s_waitcnt lgkmcnt(2)
	v_mul_f32_e32 v18, v24, v146
	v_mul_f32_e32 v28, v25, v147
	v_fmac_f32_e32 v18, v26, v148
	v_fmac_f32_e32 v28, v27, v149
	ds_read_b128 v[24:27], v7 offset:2608
	s_waitcnt lgkmcnt(2)
	v_fmac_f32_e32 v18, v98, v150
	v_fmac_f32_e32 v28, v99, v151
	v_fmac_f32_e32 v18, v100, v152
	v_fmac_f32_e32 v28, v101, v153
	ds_read_b128 v[98:101], v7 offset:2624
	s_waitcnt lgkmcnt(2)
	v_fmac_f32_e32 v18, v2, v154
	v_fmac_f32_e32 v28, v3, v155
	v_fmac_f32_e32 v18, v4, v156
	v_fmac_f32_e32 v28, v5, v157
	ds_read_b128 v[2:5], v7 offset:2640
	s_waitcnt lgkmcnt(2)
	v_fmac_f32_e32 v18, v24, v158
	v_fmac_f32_e32 v28, v25, v159
	v_fmac_f32_e32 v18, v26, v160
	v_fmac_f32_e32 v28, v27, v161
	ds_read_b128 v[24:27], v7 offset:2656
	s_waitcnt lgkmcnt(2)
	v_fmac_f32_e32 v18, v98, v162
	v_fmac_f32_e32 v28, v99, v163
	v_fmac_f32_e32 v18, v100, v164
	v_fmac_f32_e32 v28, v101, v165
	ds_read_b128 v[98:101], v7 offset:2672
	s_waitcnt lgkmcnt(2)
	v_fmac_f32_e32 v18, v2, v184
	v_fmac_f32_e32 v28, v3, v185
	v_fmac_f32_e32 v18, v4, v186
	v_fmac_f32_e32 v28, v5, v187
	ds_read_b128 v[2:5], v7 offset:2688
	s_waitcnt lgkmcnt(2)
	v_fmac_f32_e32 v18, v24, v188
	v_fmac_f32_e32 v28, v25, v189
	v_fmac_f32_e32 v18, v26, v190
	v_fmac_f32_e32 v28, v27, v191
	ds_read_b128 v[24:27], v7 offset:2704
	s_waitcnt lgkmcnt(2)
	v_fmac_f32_e32 v18, v98, v192
	v_fmac_f32_e32 v28, v99, v193
	v_fmac_f32_e32 v18, v100, v196
	v_fmac_f32_e32 v28, v101, v197
	ds_read_b128 v[98:101], v7 offset:2720
	s_waitcnt lgkmcnt(2)
	v_fmac_f32_e32 v18, v2, v198
	v_fmac_f32_e32 v28, v3, v199
	v_fmac_f32_e32 v18, v4, v200
	v_fmac_f32_e32 v28, v5, v201
	ds_read_b128 v[2:5], v7 offset:2736
	s_waitcnt lgkmcnt(2)
; template <int MODE>
; __device__ __forceinline__ void poolconv_wave(const Ctx& C, int l, int ch, int g, int lane, float* PL) {
;     ...
; #pragma unroll 2
;     for (int k4 = 0; k4 < 16; ++k4) {
;         const float w0 = wp[(4 * k4 + 0) * 64], w1 = wp[(4 * k4 + 1) * 64], w2 = wp[(4 * k4 + 2) * 64], w3 = wp[(4 * k4 + 3) * 64];
; #pragma unroll
;         for (int i = 0; i < 16; ++i) { const f32x4 pv = *(const f32x4*)(PL + i * 64 + 4 * k4); acc[i] += pv[0] * w0 + pv[1] * w1 + pv[2] * w2 + pv[3] * w3; }
;     }
	v_fmac_f32_e32 v18, v24, v202
	v_fmac_f32_e32 v28, v25, v203
	v_fmac_f32_e32 v18, v26, v204
	v_fmac_f32_e32 v28, v27, v205
	ds_read_b128 v[24:27], v7 offset:2752
	s_waitcnt lgkmcnt(2)
	v_fmac_f32_e32 v18, v98, v206
	v_fmac_f32_e32 v28, v99, v207
	v_fmac_f32_e32 v18, v100, v208
	v_fmac_f32_e32 v28, v101, v209
	ds_read_b128 v[98:101], v7 offset:2768
	s_waitcnt lgkmcnt(2)
	v_fmac_f32_e32 v18, v2, v210
	v_fmac_f32_e32 v28, v3, v211
	v_fmac_f32_e32 v18, v4, v212
	v_fmac_f32_e32 v28, v5, v213
	ds_read_b128 v[2:5], v7 offset:2784
	s_waitcnt lgkmcnt(2)
	v_fmac_f32_e32 v18, v24, v214
	v_fmac_f32_e32 v28, v25, v215
	v_fmac_f32_e32 v18, v26, v216
	v_fmac_f32_e32 v28, v27, v217
	ds_read_b128 v[24:27], v7 offset:2800
	s_waitcnt lgkmcnt(2)
	v_fmac_f32_e32 v18, v98, v218
	v_fmac_f32_e32 v28, v99, v219
	v_fmac_f32_e32 v18, v100, v220
	v_fmac_f32_e32 v28, v101, v221
	ds_read_b128 v[98:101], v7 offset:2816
	s_waitcnt lgkmcnt(2)
	v_fmac_f32_e32 v18, v2, v222
	v_fmac_f32_e32 v28, v3, v223
	v_fmac_f32_e32 v18, v4, v224
	v_fmac_f32_e32 v28, v5, v225
	ds_read_b128 v[2:5], v7 offset:2832
	s_waitcnt lgkmcnt(2)
	v_fmac_f32_e32 v18, v24, v226
	v_fmac_f32_e32 v28, v25, v227
	v_fmac_f32_e32 v18, v26, v228
	v_fmac_f32_e32 v28, v27, v229
	v_add_f32_e32 v18, v18, v28
	ds_read_b128 v[24:27], v7 offset:2848
	s_waitcnt lgkmcnt(2)
	v_mul_f32_e32 v19, v98, v146
	v_mul_f32_e32 v30, v99, v147
	v_fmac_f32_e32 v19, v100, v148
	v_fmac_f32_e32 v30, v101, v149
	ds_read_b128 v[98:101], v7 offset:2864
	s_waitcnt lgkmcnt(2)
	v_fmac_f32_e32 v19, v2, v150
	v_fmac_f32_e32 v30, v3, v151
	v_fmac_f32_e32 v19, v4, v152
	v_fmac_f32_e32 v30, v5, v153
	ds_read_b128 v[2:5], v7 offset:2880
	s_waitcnt lgkmcnt(2)
	v_fmac_f32_e32 v19, v24, v154
	v_fmac_f32_e32 v30, v25, v155
	v_fmac_f32_e32 v19, v26, v156
	v_fmac_f32_e32 v30, v27, v157
	ds_read_b128 v[24:27], v7 offset:2896
	s_waitcnt lgkmcnt(2)
	v_fmac_f32_e32 v19, v98, v158
	v_fmac_f32_e32 v30, v99, v159
	v_fmac_f32_e32 v19, v100, v160
	v_fmac_f32_e32 v30, v101, v161
	ds_read_b128 v[98:101], v7 offset:2912
	s_waitcnt lgkmcnt(2)
	v_fmac_f32_e32 v19, v2, v162
	v_fmac_f32_e32 v30, v3, v163
	v_fmac_f32_e32 v19, v4, v164
	v_fmac_f32_e32 v30, v5, v165
	ds_read_b128 v[2:5], v7 offset:2928
	s_waitcnt lgkmcnt(2)
	v_fmac_f32_e32 v19, v24, v184
	v_fmac_f32_e32 v30, v25, v185
	v_fmac_f32_e32 v19, v26, v186
	v_fmac_f32_e32 v30, v27, v187
	ds_read_b128 v[24:27], v7 offset:2944
	s_waitcnt lgkmcnt(2)
	v_fmac_f32_e32 v19, v98, v188
	v_fmac_f32_e32 v30, v99, v189
	v_fmac_f32_e32 v19, v100, v190
	v_fmac_f32_e32 v30, v101, v191
	ds_read_b128 v[98:101], v7 offset:2960
	s_waitcnt lgkmcnt(2)
	v_fmac_f32_e32 v19, v2, v192
	v_fmac_f32_e32 v30, v3, v193
	v_fmac_f32_e32 v19, v4, v196
	v_fmac_f32_e32 v30, v5, v197
	ds_read_b128 v[2:5], v7 offset:2976
	s_waitcnt lgkmcnt(2)
	v_fmac_f32_e32 v19, v24, v198
	v_fmac_f32_e32 v30, v25, v199
	v_fmac_f32_e32 v19, v26, v200
	v_fmac_f32_e32 v30, v27, v201
	ds_read_b128 v[24:27], v7 offset:2992
	s_waitcnt lgkmcnt(2)
	v_fmac_f32_e32 v19, v98, v202
	v_fmac_f32_e32 v30, v99, v203
	v_fmac_f32_e32 v19, v100, v204
	v_fmac_f32_e32 v30, v101, v205
	ds_read_b128 v[98:101], v7 offset:3008
	s_waitcnt lgkmcnt(2)
	v_fmac_f32_e32 v19, v2, v206
	v_fmac_f32_e32 v30, v3, v207
	v_fmac_f32_e32 v19, v4, v208
	v_fmac_f32_e32 v30, v5, v209
	ds_read_b128 v[2:5], v7 offset:3024
	s_waitcnt lgkmcnt(2)
	v_fmac_f32_e32 v19, v24, v210
	v_fmac_f32_e32 v30, v25, v211
	v_fmac_f32_e32 v19, v26, v212
	v_fmac_f32_e32 v30, v27, v213
	ds_read_b128 v[24:27], v7 offset:3040
	s_waitcnt lgkmcnt(2)
	v_fmac_f32_e32 v19, v98, v214
	v_fmac_f32_e32 v30, v99, v215
	v_fmac_f32_e32 v19, v100, v216
	v_fmac_f32_e32 v30, v101, v217
	ds_read_b128 v[98:101], v7 offset:3056
	s_waitcnt lgkmcnt(2)
	v_fmac_f32_e32 v19, v2, v218
	v_fmac_f32_e32 v30, v3, v219
	v_fmac_f32_e32 v19, v4, v220
	v_fmac_f32_e32 v30, v5, v221
	ds_read_b128 v[2:5], v7 offset:3072
	s_waitcnt lgkmcnt(2)
	v_fmac_f32_e32 v19, v24, v222
	v_fmac_f32_e32 v30, v25, v223
	v_fmac_f32_e32 v19, v26, v224
	v_fmac_f32_e32 v30, v27, v225
	ds_read_b128 v[24:27], v7 offset:3088
	s_waitcnt lgkmcnt(2)
	v_fmac_f32_e32 v19, v98, v226
	v_fmac_f32_e32 v30, v99, v227
	v_fmac_f32_e32 v19, v100, v228
	v_fmac_f32_e32 v30, v101, v229
	v_add_f32_e32 v19, v19, v30
	ds_read_b128 v[98:101], v7 offset:3104
	s_waitcnt lgkmcnt(2)
	v_mul_f32_e32 v20, v2, v146
	v_mul_f32_e32 v28, v3, v147
	v_fmac_f32_e32 v20, v4, v148
	v_fmac_f32_e32 v28, v5, v149
	ds_read_b128 v[2:5], v7 offset:3120
	s_waitcnt lgkmcnt(2)
	v_fmac_f32_e32 v20, v24, v150
	v_fmac_f32_e32 v28, v25, v151
	v_fmac_f32_e32 v20, v26, v152
	v_fmac_f32_e32 v28, v27, v153
	ds_read_b128 v[24:27], v7 offset:3136
	s_waitcnt lgkmcnt(2)
	v_fmac_f32_e32 v20, v98, v154
	v_fmac_f32_e32 v28, v99, v155
	v_fmac_f32_e32 v20, v100, v156
	v_fmac_f32_e32 v28, v101, v157
	ds_read_b128 v[98:101], v7 offset:3152
	s_waitcnt lgkmcnt(2)
	v_fmac_f32_e32 v20, v2, v158
	v_fmac_f32_e32 v28, v3, v159
	v_fmac_f32_e32 v20, v4, v160
	v_fmac_f32_e32 v28, v5, v161
	ds_read_b128 v[2:5], v7 offset:3168
	s_waitcnt lgkmcnt(2)
	v_fmac_f32_e32 v20, v24, v162
	v_fmac_f32_e32 v28, v25, v163
	v_fmac_f32_e32 v20, v26, v164
	v_fmac_f32_e32 v28, v27, v165
	ds_read_b128 v[24:27], v7 offset:3184
	s_waitcnt lgkmcnt(2)
	v_fmac_f32_e32 v20, v98, v184
	v_fmac_f32_e32 v28, v99, v185
	v_fmac_f32_e32 v20, v100, v186
	v_fmac_f32_e32 v28, v101, v187
	ds_read_b128 v[98:101], v7 offset:3200
	s_waitcnt lgkmcnt(2)
	v_fmac_f32_e32 v20, v2, v188
	v_fmac_f32_e32 v28, v3, v189
	v_fmac_f32_e32 v20, v4, v190
	v_fmac_f32_e32 v28, v5, v191
	ds_read_b128 v[2:5], v7 offset:3216
	s_waitcnt lgkmcnt(2)
; template <int MODE>
; __device__ __forceinline__ void poolconv_wave(const Ctx& C, int l, int ch, int g, int lane, float* PL) {
;     ...
; #pragma unroll 2
;     for (int k4 = 0; k4 < 16; ++k4) {
;         const float w0 = wp[(4 * k4 + 0) * 64], w1 = wp[(4 * k4 + 1) * 64], w2 = wp[(4 * k4 + 2) * 64], w3 = wp[(4 * k4 + 3) * 64];
; #pragma unroll
;         for (int i = 0; i < 16; ++i) { const f32x4 pv = *(const f32x4*)(PL + i * 64 + 4 * k4); acc[i] += pv[0] * w0 + pv[1] * w1 + pv[2] * w2 + pv[3] * w3; }
;     }
	v_fmac_f32_e32 v20, v24, v192
	v_fmac_f32_e32 v28, v25, v193
	v_fmac_f32_e32 v20, v26, v196
	v_fmac_f32_e32 v28, v27, v197
	ds_read_b128 v[24:27], v7 offset:3232
	s_waitcnt lgkmcnt(2)
	v_fmac_f32_e32 v20, v98, v198
	v_fmac_f32_e32 v28, v99, v199
	v_fmac_f32_e32 v20, v100, v200
	v_fmac_f32_e32 v28, v101, v201
	ds_read_b128 v[98:101], v7 offset:3248
	s_waitcnt lgkmcnt(2)
	v_fmac_f32_e32 v20, v2, v202
	v_fmac_f32_e32 v28, v3, v203
	v_fmac_f32_e32 v20, v4, v204
	v_fmac_f32_e32 v28, v5, v205
	ds_read_b128 v[2:5], v7 offset:3264
	s_waitcnt lgkmcnt(2)
	v_fmac_f32_e32 v20, v24, v206
	v_fmac_f32_e32 v28, v25, v207
	v_fmac_f32_e32 v20, v26, v208
	v_fmac_f32_e32 v28, v27, v209
	ds_read_b128 v[24:27], v7 offset:3280
	s_waitcnt lgkmcnt(2)
	v_fmac_f32_e32 v20, v98, v210
	v_fmac_f32_e32 v28, v99, v211
	v_fmac_f32_e32 v20, v100, v212
	v_fmac_f32_e32 v28, v101, v213
	ds_read_b128 v[98:101], v7 offset:3296
	s_waitcnt lgkmcnt(2)
	v_fmac_f32_e32 v20, v2, v214
	v_fmac_f32_e32 v28, v3, v215
	v_fmac_f32_e32 v20, v4, v216
	v_fmac_f32_e32 v28, v5, v217
	ds_read_b128 v[2:5], v7 offset:3312
	s_waitcnt lgkmcnt(2)
	v_fmac_f32_e32 v20, v24, v218
	v_fmac_f32_e32 v28, v25, v219
	v_fmac_f32_e32 v20, v26, v220
	v_fmac_f32_e32 v28, v27, v221
	ds_read_b128 v[24:27], v7 offset:3328
	s_waitcnt lgkmcnt(2)
	v_fmac_f32_e32 v20, v98, v222
	v_fmac_f32_e32 v28, v99, v223
	v_fmac_f32_e32 v20, v100, v224
	v_fmac_f32_e32 v28, v101, v225
	ds_read_b128 v[98:101], v7 offset:3344
	s_waitcnt lgkmcnt(2)
	v_fmac_f32_e32 v20, v2, v226
	v_fmac_f32_e32 v28, v3, v227
	v_fmac_f32_e32 v20, v4, v228
	v_fmac_f32_e32 v28, v5, v229
	v_add_f32_e32 v20, v20, v28
	ds_read_b128 v[2:5], v7 offset:3360
	s_waitcnt lgkmcnt(2)
	v_mul_f32_e32 v21, v24, v146
	v_mul_f32_e32 v30, v25, v147
	v_fmac_f32_e32 v21, v26, v148
	v_fmac_f32_e32 v30, v27, v149
	ds_read_b128 v[24:27], v7 offset:3376
	s_waitcnt lgkmcnt(2)
	v_fmac_f32_e32 v21, v98, v150
	v_fmac_f32_e32 v30, v99, v151
	v_fmac_f32_e32 v21, v100, v152
	v_fmac_f32_e32 v30, v101, v153
	ds_read_b128 v[98:101], v7 offset:3392
	s_waitcnt lgkmcnt(2)
	v_fmac_f32_e32 v21, v2, v154
	v_fmac_f32_e32 v30, v3, v155
	v_fmac_f32_e32 v21, v4, v156
	v_fmac_f32_e32 v30, v5, v157
	ds_read_b128 v[2:5], v7 offset:3408
	s_waitcnt lgkmcnt(2)
	v_fmac_f32_e32 v21, v24, v158
	v_fmac_f32_e32 v30, v25, v159
	v_fmac_f32_e32 v21, v26, v160
	v_fmac_f32_e32 v30, v27, v161
	ds_read_b128 v[24:27], v7 offset:3424
	s_waitcnt lgkmcnt(2)
	v_fmac_f32_e32 v21, v98, v162
	v_fmac_f32_e32 v30, v99, v163
	v_fmac_f32_e32 v21, v100, v164
	v_fmac_f32_e32 v30, v101, v165
	ds_read_b128 v[98:101], v7 offset:3440
	s_waitcnt lgkmcnt(2)
	v_fmac_f32_e32 v21, v2, v184
	v_fmac_f32_e32 v30, v3, v185
	v_fmac_f32_e32 v21, v4, v186
	v_fmac_f32_e32 v30, v5, v187
	ds_read_b128 v[2:5], v7 offset:3456
	s_waitcnt lgkmcnt(2)
	v_fmac_f32_e32 v21, v24, v188
	v_fmac_f32_e32 v30, v25, v189
	v_fmac_f32_e32 v21, v26, v190
	v_fmac_f32_e32 v30, v27, v191
	ds_read_b128 v[24:27], v7 offset:3472
	s_waitcnt lgkmcnt(2)
	v_fmac_f32_e32 v21, v98, v192
	v_fmac_f32_e32 v30, v99, v193
	v_fmac_f32_e32 v21, v100, v196
	v_fmac_f32_e32 v30, v101, v197
	ds_read_b128 v[98:101], v7 offset:3488
	s_waitcnt lgkmcnt(2)
	v_fmac_f32_e32 v21, v2, v198
	v_fmac_f32_e32 v30, v3, v199
	v_fmac_f32_e32 v21, v4, v200
	v_fmac_f32_e32 v30, v5, v201
	ds_read_b128 v[2:5], v7 offset:3504
	s_waitcnt lgkmcnt(2)
	v_fmac_f32_e32 v21, v24, v202
	v_fmac_f32_e32 v30, v25, v203
	v_fmac_f32_e32 v21, v26, v204
	v_fmac_f32_e32 v30, v27, v205
	ds_read_b128 v[24:27], v7 offset:3520
	s_waitcnt lgkmcnt(2)
	v_fmac_f32_e32 v21, v98, v206
	v_fmac_f32_e32 v30, v99, v207
	v_fmac_f32_e32 v21, v100, v208
	v_fmac_f32_e32 v30, v101, v209
	ds_read_b128 v[98:101], v7 offset:3536
	s_waitcnt lgkmcnt(2)
	v_fmac_f32_e32 v21, v2, v210
	v_fmac_f32_e32 v30, v3, v211
	v_fmac_f32_e32 v21, v4, v212
	v_fmac_f32_e32 v30, v5, v213
	ds_read_b128 v[2:5], v7 offset:3552
	s_waitcnt lgkmcnt(2)
	v_fmac_f32_e32 v21, v24, v214
	v_fmac_f32_e32 v30, v25, v215
	v_fmac_f32_e32 v21, v26, v216
	v_fmac_f32_e32 v30, v27, v217
	ds_read_b128 v[24:27], v7 offset:3568
	s_waitcnt lgkmcnt(2)
	v_fmac_f32_e32 v21, v98, v218
	v_fmac_f32_e32 v30, v99, v219
	v_fmac_f32_e32 v21, v100, v220
	v_fmac_f32_e32 v30, v101, v221
	ds_read_b128 v[98:101], v7 offset:3584
	s_waitcnt lgkmcnt(2)
	v_fmac_f32_e32 v21, v2, v222
	v_fmac_f32_e32 v30, v3, v223
	v_fmac_f32_e32 v21, v4, v224
	v_fmac_f32_e32 v30, v5, v225
	ds_read_b128 v[2:5], v7 offset:3600
	s_waitcnt lgkmcnt(2)
	v_fmac_f32_e32 v21, v24, v226
	v_fmac_f32_e32 v30, v25, v227
	v_fmac_f32_e32 v21, v26, v228
	v_fmac_f32_e32 v30, v27, v229
	v_add_f32_e32 v21, v21, v30
	ds_read_b128 v[24:27], v7 offset:3616
	s_waitcnt lgkmcnt(2)
	v_mul_f32_e32 v22, v98, v146
	v_mul_f32_e32 v28, v99, v147
	v_fmac_f32_e32 v22, v100, v148
	v_fmac_f32_e32 v28, v101, v149
	ds_read_b128 v[98:101], v7 offset:3632
	s_waitcnt lgkmcnt(2)
	v_fmac_f32_e32 v22, v2, v150
	v_fmac_f32_e32 v28, v3, v151
	v_fmac_f32_e32 v22, v4, v152
	v_fmac_f32_e32 v28, v5, v153
	ds_read_b128 v[2:5], v7 offset:3648
	s_waitcnt lgkmcnt(2)
	v_fmac_f32_e32 v22, v24, v154
	v_fmac_f32_e32 v28, v25, v155
	v_fmac_f32_e32 v22, v26, v156
	v_fmac_f32_e32 v28, v27, v157
	ds_read_b128 v[24:27], v7 offset:3664
	s_waitcnt lgkmcnt(2)
	v_fmac_f32_e32 v22, v98, v158
	v_fmac_f32_e32 v28, v99, v159
	v_fmac_f32_e32 v22, v100, v160
	v_fmac_f32_e32 v28, v101, v161
	ds_read_b128 v[98:101], v7 offset:3680
	s_waitcnt lgkmcnt(2)
	v_fmac_f32_e32 v22, v2, v162
	v_fmac_f32_e32 v28, v3, v163
	v_fmac_f32_e32 v22, v4, v164
	v_fmac_f32_e32 v28, v5, v165
	ds_read_b128 v[2:5], v7 offset:3696
	s_waitcnt lgkmcnt(2)
; __device__ __forceinline__ unsigned cvt_pk_bf16(float lo, float hi) { unsigned r; asm volatile("v_cvt_pk_bf16_f32 %0, %1, %2" : "=v"(r) : "v"(lo), "v"(hi)); return r; }
; template <int MODE>
; __device__ __forceinline__ void poolconv_wave(const Ctx& C, int l, int ch, int g, int lane, float* PL) {
;     ...
;     for (int k4 = 0; k4 < 16; ++k4) {
;         const float w0 = wp[(4 * k4 + 0) * 64], w1 = wp[(4 * k4 + 1) * 64], w2 = wp[(4 * k4 + 2) * 64], w3 = wp[(4 * k4 + 3) * 64];
; #pragma unroll
;         for (int i = 0; i < 16; ++i) { const f32x4 pv = *(const f32x4*)(PL + i * 64 + 4 * k4); acc[i] += pv[0] * w0 + pv[1] * w1 + pv[2] * w2 + pv[3] * w3; }
;     }
;     asm volatile("s_waitcnt lgkmcnt(0)" ::: "memory");
;     const float sc = C.in[14][l * 256 + c];
;     const bool st_out = samp || t0 == 4096;
;     float* pout = C.out + (samp ? OFF_PS + ((size_t)l * 32 + b) * 15 * 256 : OFF_PP + ((size_t)l * 4 + b) * 15 * 256) + c;
; #pragma unroll
;     for (int i = 0; i < 16; ++i) {
;         C.PRE[(rowbase + i) * DM + c] = (bf16_t)(cvt_pk_bf16(acc[i] * sc, 0.f) & 0xffffu);
	v_fmac_f32_e32 v22, v24, v184
	v_fmac_f32_e32 v28, v25, v185
	v_fmac_f32_e32 v22, v26, v186
	v_fmac_f32_e32 v28, v27, v187
	ds_read_b128 v[24:27], v7 offset:3712
	s_waitcnt lgkmcnt(2)
	v_fmac_f32_e32 v22, v98, v188
	v_fmac_f32_e32 v28, v99, v189
	v_fmac_f32_e32 v22, v100, v190
	v_fmac_f32_e32 v28, v101, v191
	ds_read_b128 v[98:101], v7 offset:3728
	s_waitcnt lgkmcnt(2)
	v_fmac_f32_e32 v22, v2, v192
	v_fmac_f32_e32 v28, v3, v193
	v_fmac_f32_e32 v22, v4, v196
	v_fmac_f32_e32 v28, v5, v197
	ds_read_b128 v[2:5], v7 offset:3744
	s_waitcnt lgkmcnt(2)
	v_fmac_f32_e32 v22, v24, v198
	v_fmac_f32_e32 v28, v25, v199
	v_fmac_f32_e32 v22, v26, v200
	v_fmac_f32_e32 v28, v27, v201
	ds_read_b128 v[24:27], v7 offset:3760
	s_waitcnt lgkmcnt(2)
	v_fmac_f32_e32 v22, v98, v202
	v_fmac_f32_e32 v28, v99, v203
	v_fmac_f32_e32 v22, v100, v204
	v_fmac_f32_e32 v28, v101, v205
	ds_read_b128 v[98:101], v7 offset:3776
	s_waitcnt lgkmcnt(2)
	v_fmac_f32_e32 v22, v2, v206
	v_fmac_f32_e32 v28, v3, v207
	v_fmac_f32_e32 v22, v4, v208
	v_fmac_f32_e32 v28, v5, v209
	ds_read_b128 v[2:5], v7 offset:3792
	s_waitcnt lgkmcnt(2)
	v_fmac_f32_e32 v22, v24, v210
	v_fmac_f32_e32 v28, v25, v211
	v_fmac_f32_e32 v22, v26, v212
	v_fmac_f32_e32 v28, v27, v213
	ds_read_b128 v[24:27], v7 offset:3808
	s_waitcnt lgkmcnt(2)
	v_fmac_f32_e32 v22, v98, v214
	v_fmac_f32_e32 v28, v99, v215
	v_fmac_f32_e32 v22, v100, v216
	v_fmac_f32_e32 v28, v101, v217
	ds_read_b128 v[98:101], v7 offset:3824
	s_waitcnt lgkmcnt(2)
	v_fmac_f32_e32 v22, v2, v218
	v_fmac_f32_e32 v28, v3, v219
	v_fmac_f32_e32 v22, v4, v220
	v_fmac_f32_e32 v28, v5, v221
	ds_read_b128 v[2:5], v7 offset:3840
	s_waitcnt lgkmcnt(2)
	v_fmac_f32_e32 v22, v24, v222
	v_fmac_f32_e32 v28, v25, v223
	v_fmac_f32_e32 v22, v26, v224
	v_fmac_f32_e32 v28, v27, v225
	ds_read_b128 v[24:27], v7 offset:3856
	s_waitcnt lgkmcnt(2)
	v_fmac_f32_e32 v22, v98, v226
	v_fmac_f32_e32 v28, v99, v227
	v_fmac_f32_e32 v22, v100, v228
	v_fmac_f32_e32 v28, v101, v229
	v_add_f32_e32 v22, v22, v28
	ds_read_b128 v[98:101], v7 offset:3872
	s_waitcnt lgkmcnt(2)
	v_mul_f32_e32 v23, v2, v146
	v_mul_f32_e32 v30, v3, v147
	v_fmac_f32_e32 v23, v4, v148
	v_fmac_f32_e32 v30, v5, v149
	ds_read_b128 v[2:5], v7 offset:3888
	s_waitcnt lgkmcnt(2)
	v_fmac_f32_e32 v23, v24, v150
	v_fmac_f32_e32 v30, v25, v151
	v_fmac_f32_e32 v23, v26, v152
	v_fmac_f32_e32 v30, v27, v153
	ds_read_b128 v[24:27], v7 offset:3904
	s_waitcnt lgkmcnt(2)
	v_fmac_f32_e32 v23, v98, v154
	v_fmac_f32_e32 v30, v99, v155
	v_fmac_f32_e32 v23, v100, v156
	v_fmac_f32_e32 v30, v101, v157
	ds_read_b128 v[98:101], v7 offset:3920
	s_waitcnt lgkmcnt(2)
	v_fmac_f32_e32 v23, v2, v158
	v_fmac_f32_e32 v30, v3, v159
	v_fmac_f32_e32 v23, v4, v160
	v_fmac_f32_e32 v30, v5, v161
	ds_read_b128 v[2:5], v7 offset:3936
	s_waitcnt lgkmcnt(2)
	v_fmac_f32_e32 v23, v24, v162
	v_fmac_f32_e32 v30, v25, v163
	v_fmac_f32_e32 v23, v26, v164
	v_fmac_f32_e32 v30, v27, v165
	ds_read_b128 v[24:27], v7 offset:3952
	s_waitcnt lgkmcnt(2)
	v_fmac_f32_e32 v23, v98, v184
	v_fmac_f32_e32 v30, v99, v185
	v_fmac_f32_e32 v23, v100, v186
	v_fmac_f32_e32 v30, v101, v187
	ds_read_b128 v[98:101], v7 offset:3968
	s_waitcnt lgkmcnt(2)
	v_fmac_f32_e32 v23, v2, v188
	v_fmac_f32_e32 v30, v3, v189
	v_fmac_f32_e32 v23, v4, v190
	v_fmac_f32_e32 v30, v5, v191
	ds_read_b128 v[2:5], v7 offset:3984
	s_waitcnt lgkmcnt(2)
	v_fmac_f32_e32 v23, v24, v192
	v_fmac_f32_e32 v30, v25, v193
	v_fmac_f32_e32 v23, v26, v196
	v_fmac_f32_e32 v30, v27, v197
	ds_read_b128 v[24:27], v7 offset:4000
	s_waitcnt lgkmcnt(2)
	v_fmac_f32_e32 v23, v98, v198
	v_fmac_f32_e32 v30, v99, v199
	v_fmac_f32_e32 v23, v100, v200
	v_fmac_f32_e32 v30, v101, v201
	ds_read_b128 v[98:101], v7 offset:4016
	s_waitcnt lgkmcnt(2)
	v_fmac_f32_e32 v23, v2, v202
	v_fmac_f32_e32 v30, v3, v203
	v_fmac_f32_e32 v23, v4, v204
	v_fmac_f32_e32 v30, v5, v205
	ds_read_b128 v[2:5], v7 offset:4032
	s_waitcnt lgkmcnt(2)
	v_fmac_f32_e32 v23, v24, v206
	v_fmac_f32_e32 v30, v25, v207
	v_fmac_f32_e32 v23, v26, v208
	v_fmac_f32_e32 v30, v27, v209
	ds_read_b128 v[24:27], v7 offset:4048
	s_waitcnt lgkmcnt(2)
	v_fmac_f32_e32 v23, v98, v210
	v_fmac_f32_e32 v30, v99, v211
	v_fmac_f32_e32 v23, v100, v212
	v_fmac_f32_e32 v30, v101, v213
	ds_read_b128 v[98:101], v7 offset:4064
	s_waitcnt lgkmcnt(2)
	v_fmac_f32_e32 v23, v2, v214
	v_fmac_f32_e32 v30, v3, v215
	v_fmac_f32_e32 v23, v4, v216
	v_fmac_f32_e32 v30, v5, v217
	ds_read_b128 v[2:5], v7 offset:4080
	s_waitcnt lgkmcnt(2)
	v_fmac_f32_e32 v23, v24, v218
	v_fmac_f32_e32 v30, v25, v219
	v_fmac_f32_e32 v23, v26, v220
	v_fmac_f32_e32 v30, v27, v221
	s_waitcnt lgkmcnt(1)
	v_fmac_f32_e32 v23, v98, v222
	v_fmac_f32_e32 v30, v99, v223
	v_fmac_f32_e32 v23, v100, v224
	v_fmac_f32_e32 v30, v101, v225
	s_waitcnt lgkmcnt(0)
	v_fmac_f32_e32 v23, v2, v226
	v_fmac_f32_e32 v30, v3, v227
	v_fmac_f32_e32 v23, v4, v228
	v_fmac_f32_e32 v30, v5, v229
	v_add_f32_e32 v23, v23, v30
	s_waitcnt lgkmcnt(0)
	global_load_dword v89, v[42:43], off
	s_cmpk_eq_i32 s22, 0x100
	s_cselect_b64 s[22:23], -1, 0
	s_add_u32 s20, s4, s24
	v_lshl_add_u64 v[2:3], v[34:35], 0, s[38:39]
	s_addc_u32 s21, s5, s25
	v_mad_i64_i32 v[98:99], s[26:27], s20, v246, v[32:33]
	s_and_b64 vcc, exec, s[22:23]
	s_waitcnt vmcnt(0)
	v_mul_f32_e32 v4, v8, v89
	v_cvt_pk_bf16_f32 v4, v4, v1
	v_mul_f32_e32 v5, v9, v89
	global_store_short v[2:3], v4, off
	v_cvt_pk_bf16_f32 v4, v5, v1
	global_store_short v[2:3], v4, off offset:2048
	s_cbranch_vccz .LBB0_636
	v_add_co_u32_e32 v4, vcc, 0xc280000, v98
	s_nop 1
	v_addc_co_u32_e32 v5, vcc, 0, v99, vcc
	global_store_dword v[4:5], v31, off
